# cross-lane reductions: ds_bpermute butterfly steps replaced by DPP row ops (xor 1,2,4,8) and v_permlane16/32_swap (xor 16,32) in LayerNorms, post, mLSTM q.n and prep
# baseline (speedup 1.0000x reference)
.LBB0_89:
	v_cmp_lt_i32_e32 vcc, s70, v28
	v_mov_b64_e32 v[4:5], v[28:29]
	v_mov_b64_e32 v[2:3], v[30:31]
	s_and_saveexec_b64 s[26:27], vcc
	v_add_u32_e32 v0, 0xffff8000, v28
	v_lshlrev_b64 v[2:3], 12, v[0:1]
	v_mov_b32_e32 v0, v28
	v_lshl_add_u64 v[2:3], s[40:41], 0, v[2:3]
	v_mov_b64_e32 v[4:5], v[0:1]
	s_or_b64 exec, exec, s[26:27]
	v_cmp_lt_i32_e32 vcc, s70, v28
	v_mov_b32_e32 v0, s11
	v_mov_b32_e32 v6, s43
	s_and_b64 vcc, s[2:3], vcc
	v_cndmask_b32_e32 v7, v0, v6, vcc
	v_mov_b32_e32 v0, s10
	v_mov_b32_e32 v6, s42
	v_cndmask_b32_e32 v6, v0, v6, vcc
	v_lshlrev_b64 v[38:39], 11, v[4:5]
	v_min_i32_e32 v0, 0x8000, v28
	v_lshl_add_u64 v[4:5], v[6:7], 0, v[38:39]
	v_lshlrev_b32_e32 v6, 1, v18
	v_mov_b32_e32 v7, v1
	v_ashrrev_i32_e32 v0, 13, v0
	s_mul_i32 s26, s44, 5
	v_lshl_add_u64 v[4:5], v[4:5], 0, v[6:7]
	v_add_u32_e32 v33, s26, v0
	global_load_dwordx2 v[16:17], v[4:5], off
	global_load_dwordx2 v[66:67], v[4:5], off offset:512
	global_load_dwordx2 v[68:69], v[4:5], off offset:1024
	global_load_dwordx2 v[70:71], v[4:5], off offset:1536
	v_mad_i64_i32 v[46:47], s[26:27], v33, s4, v[24:25]
	global_load_dwordx4 v[4:7], v[46:47], off
	global_load_dwordx4 v[8:11], v[46:47], off offset:1024
	global_load_dwordx4 v[12:15], v[46:47], off offset:2048
	v_lshlrev_b32_e32 v0, 2, v18
	global_load_dwordx4 v[46:49], v[46:47], off offset:3072
	v_lshl_add_u64 v[72:73], v[2:3], 0, v[0:1]
	global_load_dwordx4 v[50:53], v[72:73], off
	global_load_dwordx4 v[54:57], v[72:73], off offset:1024
	global_load_dwordx4 v[58:61], v[72:73], off offset:2048
	global_load_dwordx4 v[62:65], v[72:73], off offset:3072
	s_mov_b32 s26, 0x3fb504f3
	s_waitcnt vmcnt(11)
	v_lshlrev_b32_e32 v2, 16, v16
	v_and_b32_e32 v3, 0xffff0000, v16
	s_waitcnt vmcnt(10)
	v_lshlrev_b32_e32 v74, 16, v66
	v_and_b32_e32 v75, 0xffff0000, v66
	v_lshlrev_b32_e32 v66, 16, v67
	v_and_b32_e32 v67, 0xffff0000, v67
	s_waitcnt vmcnt(9)
	v_lshlrev_b32_e32 v76, 16, v68
	v_and_b32_e32 v77, 0xffff0000, v68
	v_lshlrev_b32_e32 v68, 16, v69
	v_and_b32_e32 v69, 0xffff0000, v69
	s_waitcnt vmcnt(8)
	v_lshlrev_b32_e32 v78, 16, v70
	v_and_b32_e32 v79, 0xffff0000, v70
	v_lshlrev_b32_e32 v70, 16, v71
	v_and_b32_e32 v71, 0xffff0000, v71
	s_waitcnt vmcnt(7)
	v_pk_mul_f32 v[2:3], v[4:5], v[2:3]
	v_lshlrev_b32_e32 v16, 16, v17
	v_and_b32_e32 v17, 0xffff0000, v17
	s_waitcnt vmcnt(6)
	v_pk_mul_f32 v[4:5], v[10:11], v[66:67]
	s_waitcnt vmcnt(5)
	v_pk_mul_f32 v[10:11], v[14:15], v[68:69]
	s_waitcnt vmcnt(4)
	v_pk_mul_f32 v[14:15], v[48:49], v[70:71]
	s_waitcnt vmcnt(3)
	v_pk_fma_f32 v[48:49], v[50:51], s[26:27], v[2:3] op_sel_hi:[1,0,1]
	v_pk_mul_f32 v[6:7], v[6:7], v[16:17]
	v_add_f32_e32 v2, 0, v48
	v_pk_mul_f32 v[16:17], v[46:47], v[78:79]
	v_pk_fma_f32 v[46:47], v[52:53], s[26:27], v[6:7] op_sel_hi:[1,0,1]
	v_add_f32_e32 v2, v49, v2
	v_pk_mul_f32 v[8:9], v[8:9], v[74:75]
	v_add_f32_e32 v2, v46, v2
	s_waitcnt vmcnt(2)
	v_pk_fma_f32 v[52:53], v[54:55], s[26:27], v[8:9] op_sel_hi:[1,0,1]
	v_add_f32_e32 v2, v47, v2
	v_add_f32_e32 v2, v52, v2
	v_pk_fma_f32 v[50:51], v[56:57], s[26:27], v[4:5] op_sel_hi:[1,0,1]
	v_add_f32_e32 v2, v53, v2
	v_pk_mul_f32 v[12:13], v[12:13], v[76:77]
	v_add_f32_e32 v2, v50, v2
	s_waitcnt vmcnt(1)
	v_pk_fma_f32 v[12:13], v[58:59], s[26:27], v[12:13] op_sel_hi:[1,0,1]
	v_add_f32_e32 v2, v51, v2
	v_add_f32_e32 v2, v12, v2
	v_pk_fma_f32 v[10:11], v[60:61], s[26:27], v[10:11] op_sel_hi:[1,0,1]
	v_add_f32_e32 v2, v13, v2
	v_add_f32_e32 v2, v10, v2
	s_waitcnt vmcnt(0)
	v_pk_fma_f32 v[16:17], v[62:63], s[26:27], v[16:17] op_sel_hi:[1,0,1]
	v_add_f32_e32 v2, v11, v2
	v_add_f32_e32 v2, v16, v2
	v_pk_fma_f32 v[14:15], v[64:65], s[26:27], v[14:15] op_sel_hi:[1,0,1]
	v_add_f32_e32 v2, v17, v2
	v_add_f32_e32 v2, v14, v2
	v_add_f32_e32 v2, v15, v2
	v_mov_b32_e32 v3, v2
	s_nop 1
	v_permlane32_swap_b32_e32 v3, v2
	s_waitcnt lgkmcnt(0)
	v_add_f32_e32 v2, v2, v3
	v_mov_b32_e32 v3, v2
	s_nop 1
	v_permlane16_swap_b32_e32 v3, v2
	s_waitcnt lgkmcnt(0)
	v_add_f32_e32 v2, v2, v3
	s_nop 1
	v_mov_b32_dpp v3, v2 row_ror:8 row_mask:0xf bank_mask:0xf
	s_waitcnt lgkmcnt(0)
	v_add_f32_e32 v2, v2, v3
	s_nop 1
	v_mov_b32_dpp v3, v2 quad_perm:[3,2,1,0] row_mask:0xf bank_mask:0xf
	s_nop 1
	v_mov_b32_dpp v3, v3 row_half_mirror row_mask:0xf bank_mask:0xf
	s_waitcnt lgkmcnt(0)
	v_add_f32_e32 v2, v2, v3
	s_nop 1
	v_mov_b32_dpp v3, v2 quad_perm:[2,3,0,1] row_mask:0xf bank_mask:0xf
	s_waitcnt lgkmcnt(0)
	v_add_f32_e32 v35, v2, v3
	s_nop 1
	v_mov_b32_dpp v37, v35 quad_perm:[1,0,3,2] row_mask:0xf bank_mask:0xf
	s_waitcnt lgkmcnt(0)
	v_add_f32_e32 v35, v35, v37
	v_mul_f32_e32 v54, 0x3a800000, v35
	v_pk_add_f32 v[48:49], v[48:49], v[54:55] op_sel_hi:[1,0] neg_lo:[0,1] neg_hi:[0,1]
	v_pk_add_f32 v[46:47], v[46:47], v[54:55] op_sel_hi:[1,0] neg_lo:[0,1] neg_hi:[0,1]
	v_pk_add_f32 v[58:59], v[10:11], v[54:55] op_sel_hi:[1,0] neg_lo:[0,1] neg_hi:[0,1]
	v_pk_mul_f32 v[10:11], v[48:49], v[48:49]
	v_pk_add_f32 v[56:57], v[12:13], v[54:55] op_sel_hi:[1,0] neg_lo:[0,1] neg_hi:[0,1]
	v_pk_mul_f32 v[12:13], v[46:47], v[46:47]
	v_add_f32_e32 v10, v10, v11
	v_pk_add_f32 v[52:53], v[52:53], v[54:55] op_sel_hi:[1,0] neg_lo:[0,1] neg_hi:[0,1]
	v_add_f32_e32 v10, v12, v10
	v_pk_add_f32 v[50:51], v[50:51], v[54:55] op_sel_hi:[1,0] neg_lo:[0,1] neg_hi:[0,1]
	v_pk_add_f32 v[60:61], v[16:17], v[54:55] op_sel_hi:[1,0] neg_lo:[0,1] neg_hi:[0,1]
	v_pk_add_f32 v[54:55], v[14:15], v[54:55] op_sel_hi:[1,0] neg_lo:[0,1] neg_hi:[0,1]
	v_pk_mul_f32 v[14:15], v[52:53], v[52:53]
	v_add_f32_e32 v10, v13, v10
	v_add_f32_e32 v10, v14, v10
	v_pk_mul_f32 v[16:17], v[50:51], v[50:51]
	v_add_f32_e32 v10, v15, v10
	v_add_f32_e32 v10, v16, v10
	v_pk_mul_f32 v[62:63], v[56:57], v[56:57]
	v_add_f32_e32 v10, v17, v10
	v_add_f32_e32 v10, v62, v10
	v_pk_mul_f32 v[64:65], v[58:59], v[58:59]
	v_add_f32_e32 v10, v63, v10
	v_add_f32_e32 v10, v64, v10
	v_pk_mul_f32 v[66:67], v[60:61], v[60:61]
	v_add_f32_e32 v10, v65, v10
	v_add_f32_e32 v10, v66, v10
	v_pk_mul_f32 v[68:69], v[54:55], v[54:55]
	v_add_f32_e32 v10, v67, v10
	v_add_f32_e32 v10, v68, v10
	v_add_f32_e32 v10, v69, v10
	v_mov_b32_e32 v11, v10
	s_nop 1
	v_permlane32_swap_b32_e32 v11, v10
	s_waitcnt lgkmcnt(0)
	v_add_f32_e32 v10, v10, v11
	v_mov_b32_e32 v11, v10
	s_nop 1
	v_permlane16_swap_b32_e32 v11, v10
	s_waitcnt lgkmcnt(0)
	v_add_f32_e32 v10, v10, v11
	s_nop 1
	v_mov_b32_dpp v11, v10 row_ror:8 row_mask:0xf bank_mask:0xf
	s_waitcnt lgkmcnt(0)
	v_add_f32_e32 v10, v10, v11
	s_nop 1
	v_mov_b32_dpp v11, v10 quad_perm:[3,2,1,0] row_mask:0xf bank_mask:0xf
	s_nop 1
	v_mov_b32_dpp v11, v11 row_half_mirror row_mask:0xf bank_mask:0xf
	s_waitcnt lgkmcnt(0)
	v_add_f32_e32 v10, v10, v11
	s_nop 1
	v_mov_b32_dpp v11, v10 quad_perm:[2,3,0,1] row_mask:0xf bank_mask:0xf
	s_waitcnt lgkmcnt(0)
	v_add_f32_e32 v10, v10, v11
	s_nop 1
	v_mov_b32_dpp v11, v10 quad_perm:[1,0,3,2] row_mask:0xf bank_mask:0xf
	s_waitcnt lgkmcnt(0)
	v_add_f32_e32 v10, v10, v11
	v_fmamk_f32 v10, v10, 0x3a800000, v208
	v_mul_f32_e32 v11, 0x4b800000, v10
	v_cmp_gt_f32_e32 vcc, s5, v10
	s_nop 1
	v_cndmask_b32_e32 v10, v10, v11, vcc
	v_rsq_f32_e32 v10, v10
	s_nop 0
	v_mul_f32_e32 v11, 0x45800000, v10
	v_cndmask_b32_e32 v62, v10, v11, vcc
	v_pk_mul_f32 v[10:11], v[48:49], v[62:63] op_sel_hi:[1,0]
	v_pk_mul_f32 v[12:13], v[46:47], v[62:63] op_sel_hi:[1,0]
	v_pk_fma_f32 v[2:3], v[80:81], v[10:11], v[96:97]
	v_pk_fma_f32 v[4:5], v[82:83], v[12:13], v[98:99]
	global_store_dwordx4 v[72:73], v[2:5], off
	v_pk_mul_f32 v[14:15], v[52:53], v[62:63] op_sel_hi:[1,0]
	v_pk_mul_f32 v[16:17], v[50:51], v[62:63] op_sel_hi:[1,0]
	v_pk_mul_f32 v[46:47], v[56:57], v[62:63] op_sel_hi:[1,0]
	v_pk_mul_f32 v[48:49], v[58:59], v[62:63] op_sel_hi:[1,0]
	v_pk_mul_f32 v[50:51], v[60:61], v[62:63] op_sel_hi:[1,0]
	v_pk_mul_f32 v[52:53], v[54:55], v[62:63] op_sel_hi:[1,0]
	s_andn2_b64 vcc, exec, s[12:13]
	v_pk_fma_f32 v[6:7], v[84:85], v[14:15], v[100:101]
	v_pk_fma_f32 v[8:9], v[86:87], v[16:17], v[102:103]
	global_store_dwordx4 v[72:73], v[6:9], off offset:1024
	v_pk_fma_f32 v[10:11], v[88:89], v[46:47], v[104:105]
	v_pk_fma_f32 v[12:13], v[90:91], v[48:49], v[106:107]
	global_store_dwordx4 v[72:73], v[10:13], off offset:2048
	v_pk_fma_f32 v[14:15], v[92:93], v[50:51], v[108:109]
	v_pk_fma_f32 v[16:17], v[94:95], v[52:53], v[110:111]
	global_store_dwordx4 v[72:73], v[14:17], off offset:3072
	s_cbranch_vccnz .LBB0_88
	v_add_f32_e32 v35, 0, v2
	v_add_f32_e32 v35, v3, v35
	v_add_f32_e32 v35, v4, v35
	v_add_f32_e32 v35, v5, v35
	v_add_f32_e32 v35, v6, v35
	v_add_f32_e32 v35, v7, v35
	v_add_f32_e32 v35, v8, v35
	v_add_f32_e32 v35, v9, v35
	v_add_f32_e32 v35, v10, v35
	v_add_f32_e32 v35, v11, v35
	v_add_f32_e32 v35, v12, v35
	v_add_f32_e32 v35, v13, v35
	v_add_f32_e32 v35, v14, v35
	v_add_f32_e32 v35, v15, v35
	v_add_f32_e32 v35, v16, v35
	v_add_f32_e32 v35, v17, v35
	v_mov_b32_e32 v37, v35
	s_nop 1
	v_permlane32_swap_b32_e32 v37, v35
	v_add_u32_e32 v33, 5, v33
	v_mov_b64_e32 v[46:47], s[18:19]
	v_mad_i64_i32 v[50:51], s[26:27], v33, s4, v[46:47]
	s_waitcnt lgkmcnt(0)
	v_add_f32_e32 v35, v35, v37
	v_mov_b32_e32 v37, v35
	s_nop 1
	v_permlane16_swap_b32_e32 v37, v35
	s_mov_b64 s[26:27], 0x1000
	v_lshl_add_u64 v[54:55], v[50:51], 0, s[26:27]
	v_lshl_add_u64 v[46:47], v[54:55], 0, v[0:1]
	global_load_dwordx4 v[112:115], v[46:47], off
	global_load_dwordx4 v[116:119], v[46:47], off offset:1024
	global_load_dwordx4 v[120:123], v[46:47], off offset:2048
	global_load_dwordx4 v[124:127], v[46:47], off offset:3072
	s_waitcnt lgkmcnt(0)
	v_add_f32_e32 v35, v35, v37
	s_nop 1
	v_mov_b32_dpp v37, v35 row_ror:8 row_mask:0xf bank_mask:0xf
	v_lshl_add_u64 v[56:57], v[50:51], 0, v[0:1]
	global_load_dwordx4 v[128:131], v[56:57], off
	global_load_dwordx4 v[132:135], v[56:57], off offset:1024
	global_load_dwordx4 v[136:139], v[56:57], off offset:2048
	global_load_dwordx4 v[140:143], v[56:57], off offset:3072
	v_lshl_add_u64 v[38:39], v[26:27], 0, v[38:39]
	s_waitcnt lgkmcnt(0)
	v_add_f32_e32 v35, v35, v37
	s_nop 1
	v_mov_b32_dpp v37, v35 quad_perm:[3,2,1,0] row_mask:0xf bank_mask:0xf
	s_nop 1
	v_mov_b32_dpp v37, v37 row_half_mirror row_mask:0xf bank_mask:0xf
	s_waitcnt lgkmcnt(0)
	v_add_f32_e32 v35, v35, v37
	s_nop 1
	v_mov_b32_dpp v37, v35 quad_perm:[2,3,0,1] row_mask:0xf bank_mask:0xf
	s_waitcnt lgkmcnt(0)
	v_add_f32_e32 v33, v35, v37
	s_nop 1
	v_mov_b32_dpp v35, v33 quad_perm:[1,0,3,2] row_mask:0xf bank_mask:0xf
	v_mov_b32_e32 v37, v1
	s_waitcnt lgkmcnt(0)
	v_add_f32_e32 v0, v33, v35
	v_mul_f32_e32 v0, 0x3a800000, v0
	v_pk_add_f32 v[2:3], v[2:3], v[0:1] op_sel_hi:[1,0] neg_lo:[0,1] neg_hi:[0,1]
	v_pk_add_f32 v[4:5], v[4:5], v[0:1] op_sel_hi:[1,0] neg_lo:[0,1] neg_hi:[0,1]
	v_pk_add_f32 v[58:59], v[8:9], v[0:1] op_sel_hi:[1,0] neg_lo:[0,1] neg_hi:[0,1]
	v_pk_mul_f32 v[8:9], v[2:3], v[2:3]
	v_pk_add_f32 v[60:61], v[6:7], v[0:1] op_sel_hi:[1,0] neg_lo:[0,1] neg_hi:[0,1]
	v_pk_add_f32 v[12:13], v[12:13], v[0:1] op_sel_hi:[1,0] neg_lo:[0,1] neg_hi:[0,1]
	v_pk_add_f32 v[10:11], v[10:11], v[0:1] op_sel_hi:[1,0] neg_lo:[0,1] neg_hi:[0,1]
	v_pk_add_f32 v[16:17], v[16:17], v[0:1] op_sel_hi:[1,0] neg_lo:[0,1] neg_hi:[0,1]
	v_pk_add_f32 v[14:15], v[14:15], v[0:1] op_sel_hi:[1,0] neg_lo:[0,1] neg_hi:[0,1]
	v_pk_mul_f32 v[6:7], v[4:5], v[4:5]
	v_add_f32_e32 v0, v8, v9
	v_add_f32_e32 v0, v6, v0
	v_pk_mul_f32 v[64:65], v[60:61], v[60:61]
	v_add_f32_e32 v0, v7, v0
	v_add_f32_e32 v0, v64, v0
	v_pk_mul_f32 v[62:63], v[58:59], v[58:59]
	v_add_f32_e32 v0, v65, v0
	v_add_f32_e32 v0, v62, v0
	v_pk_mul_f32 v[68:69], v[10:11], v[10:11]
	v_add_f32_e32 v0, v63, v0
	v_add_f32_e32 v0, v68, v0
	v_pk_mul_f32 v[66:67], v[12:13], v[12:13]
	v_add_f32_e32 v0, v69, v0
	v_add_f32_e32 v0, v66, v0
	v_pk_mul_f32 v[72:73], v[14:15], v[14:15]
	v_add_f32_e32 v0, v67, v0
	v_add_f32_e32 v0, v72, v0
	v_pk_mul_f32 v[70:71], v[16:17], v[16:17]
	v_add_f32_e32 v0, v73, v0
	v_add_f32_e32 v0, v70, v0
	v_add_f32_e32 v0, v71, v0
	v_mov_b32_e32 v6, v0
	s_nop 1
	v_permlane32_swap_b32_e32 v6, v0
	v_mov_b32_e32 v33, v1
	v_mov_b32_e32 v35, v1
	s_waitcnt lgkmcnt(0)
	v_add_f32_e32 v0, v0, v6
	v_mov_b32_e32 v6, v0
	s_nop 1
	v_permlane16_swap_b32_e32 v6, v0
	s_waitcnt lgkmcnt(0)
	v_add_f32_e32 v0, v0, v6
	s_nop 1
	v_mov_b32_dpp v6, v0 row_ror:8 row_mask:0xf bank_mask:0xf
	s_waitcnt lgkmcnt(0)
	v_add_f32_e32 v0, v0, v6
	s_nop 1
	v_mov_b32_dpp v6, v0 quad_perm:[3,2,1,0] row_mask:0xf bank_mask:0xf
	s_nop 1
	v_mov_b32_dpp v6, v6 row_half_mirror row_mask:0xf bank_mask:0xf
	s_waitcnt vmcnt(0)
	v_pk_add_f32 v[8:9], v[114:115], 1.0 op_sel_hi:[1,0]
	s_waitcnt lgkmcnt(0)
	v_add_f32_e32 v0, v0, v6
	s_nop 1
	v_mov_b32_dpp v6, v0 quad_perm:[2,3,0,1] row_mask:0xf bank_mask:0xf
	v_pk_add_f32 v[46:47], v[112:113], 1.0 op_sel_hi:[1,0]
	s_waitcnt lgkmcnt(0)
	v_add_f32_e32 v0, v0, v6
	s_nop 1
	v_mov_b32_dpp v6, v0 quad_perm:[1,0,3,2] row_mask:0xf bank_mask:0xf
	s_waitcnt lgkmcnt(0)
	v_add_f32_e32 v0, v0, v6
	v_fmamk_f32 v0, v0, 0x3a800000, v208
	v_mul_f32_e32 v6, 0x4b800000, v0
	v_cmp_gt_f32_e32 vcc, s5, v0
	s_nop 1
	v_cndmask_b32_e32 v0, v0, v6, vcc
	v_rsq_f32_e32 v0, v0
	v_lshl_add_u64 v[6:7], v[54:55], 0, v[32:33]
	v_mul_f32_e32 v33, 0x45800000, v0
	v_cndmask_b32_e32 v0, v0, v33, vcc
	v_pk_mul_f32 v[2:3], v[2:3], v[0:1] op_sel_hi:[1,0]
	v_pk_mul_f32 v[4:5], v[4:5], v[0:1] op_sel_hi:[1,0]
	v_pk_fma_f32 v[2:3], v[46:47], v[2:3], v[128:129]
	v_pk_fma_f32 v[4:5], v[8:9], v[4:5], v[130:131]
	v_cvt_pk_bf16_f32 v2, v2, v3
	v_cvt_pk_bf16_f32 v3, v4, v5
	global_store_dwordx2 v[38:39], v[2:3], off
	v_pk_mul_f32 v[48:49], v[60:61], v[0:1] op_sel_hi:[1,0]
	v_pk_mul_f32 v[50:51], v[58:59], v[0:1] op_sel_hi:[1,0]
	v_lshl_add_u64 v[46:47], v[54:55], 0, v[34:35]
	v_pk_mul_f32 v[10:11], v[10:11], v[0:1] op_sel_hi:[1,0]
	v_pk_mul_f32 v[12:13], v[12:13], v[0:1] op_sel_hi:[1,0]
	v_pk_add_f32 v[2:3], v[116:117], 1.0 op_sel_hi:[1,0]
	v_pk_add_f32 v[4:5], v[118:119], 1.0 op_sel_hi:[1,0]
	v_pk_fma_f32 v[2:3], v[2:3], v[48:49], v[132:133]
	v_pk_fma_f32 v[4:5], v[4:5], v[50:51], v[134:135]
	v_cvt_pk_bf16_f32 v2, v2, v3
	v_cvt_pk_bf16_f32 v3, v4, v5
	global_store_dwordx2 v[38:39], v[2:3], off offset:512
	v_lshl_add_u64 v[46:47], v[54:55], 0, v[36:37]
	v_pk_add_f32 v[2:3], v[120:121], 1.0 op_sel_hi:[1,0]
	v_pk_add_f32 v[4:5], v[122:123], 1.0 op_sel_hi:[1,0]
	v_pk_fma_f32 v[2:3], v[2:3], v[10:11], v[136:137]
	v_pk_fma_f32 v[4:5], v[4:5], v[12:13], v[138:139]
	v_cvt_pk_bf16_f32 v2, v2, v3
	v_cvt_pk_bf16_f32 v3, v4, v5
	global_store_dwordx2 v[38:39], v[2:3], off offset:1024
	v_pk_mul_f32 v[10:11], v[14:15], v[0:1] op_sel_hi:[1,0]
	v_pk_mul_f32 v[12:13], v[16:17], v[0:1] op_sel_hi:[1,0]
	v_pk_add_f32 v[2:3], v[124:125], 1.0 op_sel_hi:[1,0]
	v_pk_add_f32 v[4:5], v[126:127], 1.0 op_sel_hi:[1,0]
	v_pk_fma_f32 v[2:3], v[2:3], v[10:11], v[140:141]
	v_pk_fma_f32 v[4:5], v[4:5], v[12:13], v[142:143]
	v_cvt_pk_bf16_f32 v2, v2, v3
	v_cvt_pk_bf16_f32 v3, v4, v5
	global_store_dwordx2 v[38:39], v[2:3], off offset:1536
	s_branch .LBB0_88

.LBB0_263:
	s_or_b64 exec, exec, s[26:27]
	v_lshlrev_b64 v[22:23], 11, v[22:23]
	v_min_i32_e32 v17, 0x8000, v12
	v_lshl_add_u64 v[34:35], v[8:9], 0, v[22:23]
	v_ashrrev_i32_e32 v17, 13, v17
	s_mul_i32 s26, s44, 5
	global_load_dwordx2 v[66:67], v[34:35], off offset:1536
	global_load_dwordx2 v[68:69], v[34:35], off
	global_load_dwordx2 v[70:71], v[34:35], off offset:512
	v_add_u32_e32 v17, s26, v17
	v_mad_i64_i32 v[46:47], s[26:27], v17, s4, v[6:7]
	global_load_dwordx2 v[72:73], v[34:35], off offset:1024
	s_nop 0
	global_load_dwordx4 v[34:37], v[46:47], off offset:3072
	global_load_dwordx4 v[38:41], v[46:47], off
	global_load_dwordx4 v[42:45], v[46:47], off offset:1024
	s_nop 0
	global_load_dwordx4 v[46:49], v[46:47], off offset:2048
	v_lshl_add_u64 v[26:27], v[26:27], 0, v[0:1]
	global_load_dwordx4 v[50:53], v[26:27], off offset:3072
	global_load_dwordx4 v[54:57], v[26:27], off
	global_load_dwordx4 v[58:61], v[26:27], off offset:1024
	global_load_dwordx4 v[62:65], v[26:27], off offset:2048
	s_mov_b32 s26, 0x3fb504f3
	v_lshl_add_u64 v[12:13], v[12:13], 0, s[12:13]
	v_lshl_add_u64 v[14:15], v[14:15], 0, s[2:3]
	s_waitcnt vmcnt(0)
	v_and_b32_e32 v27, 0xffff0000, v66
	v_lshlrev_b32_e32 v26, 16, v66
	v_and_b32_e32 v75, 0xffff0000, v67
	v_lshlrev_b32_e32 v74, 16, v67
	v_lshlrev_b32_e32 v66, 16, v68
	v_and_b32_e32 v67, 0xffff0000, v68
	v_pk_mul_f32 v[26:27], v[34:35], v[26:27]
	v_pk_mul_f32 v[34:35], v[36:37], v[74:75]
	v_pk_mul_f32 v[36:37], v[38:39], v[66:67]
	v_lshlrev_b32_e32 v68, 16, v69
	v_and_b32_e32 v69, 0xffff0000, v69
	v_pk_fma_f32 v[26:27], v[50:51], s[26:27], v[26:27] op_sel_hi:[1,0,1]
	v_pk_fma_f32 v[50:51], v[54:55], s[26:27], v[36:37] op_sel_hi:[1,0,1]
	v_lshlrev_b32_e32 v76, 16, v70
	v_and_b32_e32 v77, 0xffff0000, v70
	v_lshlrev_b32_e32 v70, 16, v71
	v_and_b32_e32 v71, 0xffff0000, v71
	v_lshlrev_b32_e32 v78, 16, v72
	v_and_b32_e32 v79, 0xffff0000, v72
	v_lshlrev_b32_e32 v72, 16, v73
	v_and_b32_e32 v73, 0xffff0000, v73
	v_pk_mul_f32 v[38:39], v[40:41], v[68:69]
	v_add_f32_e32 v19, 0, v50
	v_pk_mul_f32 v[40:41], v[42:43], v[76:77]
	v_pk_mul_f32 v[42:43], v[44:45], v[70:71]
	v_pk_mul_f32 v[44:45], v[46:47], v[78:79]
	v_pk_mul_f32 v[46:47], v[48:49], v[72:73]
	v_pk_fma_f32 v[48:49], v[52:53], s[26:27], v[34:35] op_sel_hi:[1,0,1]
	v_pk_fma_f32 v[52:53], v[56:57], s[26:27], v[38:39] op_sel_hi:[1,0,1]
	v_add_f32_e32 v19, v51, v19
	v_add_f32_e32 v19, v52, v19
	v_pk_fma_f32 v[54:55], v[58:59], s[26:27], v[40:41] op_sel_hi:[1,0,1]
	v_add_f32_e32 v19, v53, v19
	v_add_f32_e32 v19, v54, v19
	v_pk_fma_f32 v[42:43], v[60:61], s[26:27], v[42:43] op_sel_hi:[1,0,1]
	v_add_f32_e32 v19, v55, v19
	v_add_f32_e32 v19, v42, v19
	v_pk_fma_f32 v[44:45], v[62:63], s[26:27], v[44:45] op_sel_hi:[1,0,1]
	v_add_f32_e32 v19, v43, v19
	v_add_f32_e32 v19, v44, v19
	v_pk_fma_f32 v[46:47], v[64:65], s[26:27], v[46:47] op_sel_hi:[1,0,1]
	v_add_f32_e32 v19, v45, v19
	v_add_f32_e32 v19, v46, v19
	v_add_f32_e32 v19, v47, v19
	v_add_f32_e32 v19, v26, v19
	v_add_f32_e32 v19, v27, v19
	v_add_f32_e32 v19, v48, v19
	v_add_f32_e32 v19, v49, v19
	v_mov_b32_e32 v21, v19
	s_nop 1
	v_permlane32_swap_b32_e32 v21, v19
	global_load_dwordx4 v[34:37], v[2:3], off
	global_load_dwordx4 v[38:41], v[4:5], off
	s_waitcnt lgkmcnt(0)
	v_add_f32_e32 v19, v19, v21
	v_mov_b32_e32 v21, v19
	s_nop 1
	v_permlane16_swap_b32_e32 v21, v19
	s_waitcnt lgkmcnt(0)
	v_add_f32_e32 v19, v19, v21
	s_nop 1
	v_mov_b32_dpp v21, v19 row_ror:8 row_mask:0xf bank_mask:0xf
	s_waitcnt lgkmcnt(0)
	v_add_f32_e32 v19, v19, v21
	s_nop 1
	v_mov_b32_dpp v21, v19 quad_perm:[3,2,1,0] row_mask:0xf bank_mask:0xf
	s_nop 1
	v_mov_b32_dpp v21, v21 row_half_mirror row_mask:0xf bank_mask:0xf
	s_waitcnt lgkmcnt(0)
	v_add_f32_e32 v19, v19, v21
	s_nop 1
	v_mov_b32_dpp v21, v19 quad_perm:[2,3,0,1] row_mask:0xf bank_mask:0xf
	s_waitcnt lgkmcnt(0)
	v_add_f32_e32 v19, v19, v21
	s_nop 1
	v_mov_b32_dpp v21, v19 quad_perm:[1,0,3,2] row_mask:0xf bank_mask:0xf
	s_waitcnt lgkmcnt(0)
	v_add_f32_e32 v19, v19, v21
	v_mul_f32_e32 v56, 0x3a800000, v19
	v_pk_add_f32 v[50:51], v[50:51], v[56:57] op_sel_hi:[1,0] neg_lo:[0,1] neg_hi:[0,1]
	v_pk_add_f32 v[52:53], v[52:53], v[56:57] op_sel_hi:[1,0] neg_lo:[0,1] neg_hi:[0,1]
	v_pk_add_f32 v[60:61], v[26:27], v[56:57] op_sel_hi:[1,0] neg_lo:[0,1] neg_hi:[0,1]
	v_pk_mul_f32 v[26:27], v[50:51], v[50:51]
	v_pk_add_f32 v[58:59], v[44:45], v[56:57] op_sel_hi:[1,0] neg_lo:[0,1] neg_hi:[0,1]
	v_pk_mul_f32 v[44:45], v[52:53], v[52:53]
	v_add_f32_e32 v19, v26, v27
	v_pk_add_f32 v[54:55], v[54:55], v[56:57] op_sel_hi:[1,0] neg_lo:[0,1] neg_hi:[0,1]
	v_add_f32_e32 v19, v44, v19
	v_pk_add_f32 v[42:43], v[42:43], v[56:57] op_sel_hi:[1,0] neg_lo:[0,1] neg_hi:[0,1]
	v_pk_add_f32 v[46:47], v[46:47], v[56:57] op_sel_hi:[1,0] neg_lo:[0,1] neg_hi:[0,1]
	v_pk_add_f32 v[56:57], v[48:49], v[56:57] op_sel_hi:[1,0] neg_lo:[0,1] neg_hi:[0,1]
	v_pk_mul_f32 v[48:49], v[54:55], v[54:55]
	v_add_f32_e32 v19, v45, v19
	v_add_f32_e32 v19, v48, v19
	v_pk_mul_f32 v[62:63], v[42:43], v[42:43]
	v_add_f32_e32 v19, v49, v19
	v_add_f32_e32 v19, v62, v19
	v_pk_mul_f32 v[64:65], v[58:59], v[58:59]
	v_add_f32_e32 v19, v63, v19
	v_add_f32_e32 v19, v64, v19
	v_pk_mul_f32 v[66:67], v[46:47], v[46:47]
	v_add_f32_e32 v19, v65, v19
	v_add_f32_e32 v19, v66, v19
	v_pk_mul_f32 v[68:69], v[60:61], v[60:61]
	v_add_f32_e32 v19, v67, v19
	v_add_f32_e32 v19, v68, v19
	v_pk_mul_f32 v[70:71], v[56:57], v[56:57]
	v_add_f32_e32 v19, v69, v19
	v_add_f32_e32 v19, v70, v19
	v_add_f32_e32 v19, v71, v19
	v_mov_b32_e32 v21, v19
	s_nop 1
	v_permlane32_swap_b32_e32 v21, v19
	v_lshl_add_u64 v[62:63], v[24:25], 0, v[0:1]
	s_waitcnt lgkmcnt(0)
	v_add_f32_e32 v19, v19, v21
	v_mov_b32_e32 v21, v19
	s_nop 1
	v_permlane16_swap_b32_e32 v21, v19
	s_waitcnt lgkmcnt(0)
	v_add_f32_e32 v19, v19, v21
	s_nop 1
	v_mov_b32_dpp v21, v19 row_ror:8 row_mask:0xf bank_mask:0xf
	s_waitcnt lgkmcnt(0)
	v_add_f32_e32 v19, v19, v21
	s_nop 1
	v_mov_b32_dpp v21, v19 quad_perm:[3,2,1,0] row_mask:0xf bank_mask:0xf
	s_nop 1
	v_mov_b32_dpp v21, v21 row_half_mirror row_mask:0xf bank_mask:0xf
	s_waitcnt lgkmcnt(0)
	v_add_f32_e32 v19, v19, v21
	s_nop 1
	v_mov_b32_dpp v21, v19 quad_perm:[2,3,0,1] row_mask:0xf bank_mask:0xf
	s_waitcnt lgkmcnt(0)
	v_add_f32_e32 v19, v19, v21
	s_nop 1
	v_mov_b32_dpp v21, v19 quad_perm:[1,0,3,2] row_mask:0xf bank_mask:0xf
	s_waitcnt lgkmcnt(0)
	v_add_f32_e32 v19, v19, v21
	v_fmamk_f32 v19, v19, 0x3a800000, v208
	v_mul_f32_e32 v21, 0x4b800000, v19
	v_cmp_gt_f32_e32 vcc, s5, v19
	s_nop 1
	v_cndmask_b32_e32 v19, v19, v21, vcc
	v_rsq_f32_e32 v19, v19
	s_nop 0
	v_mul_f32_e32 v21, 0x45800000, v19
	v_cndmask_b32_e32 v64, v19, v21, vcc
	v_pk_mul_f32 v[24:25], v[50:51], v[64:65] op_sel_hi:[1,0]
	v_pk_mul_f32 v[26:27], v[52:53], v[64:65] op_sel_hi:[1,0]
	s_waitcnt vmcnt(0)
	v_pk_fma_f32 v[24:25], v[34:35], v[24:25], v[38:39]
	v_pk_fma_f32 v[26:27], v[36:37], v[26:27], v[40:41]
	global_store_dwordx4 v[62:63], v[24:27], off
	global_load_dwordx4 v[34:37], v[2:3], off offset:1024
	global_load_dwordx4 v[38:41], v[4:5], off offset:1024
	v_pk_mul_f32 v[44:45], v[54:55], v[64:65] op_sel_hi:[1,0]
	v_pk_mul_f32 v[42:43], v[42:43], v[64:65] op_sel_hi:[1,0]
	v_pk_mul_f32 v[48:49], v[58:59], v[64:65] op_sel_hi:[1,0]
	v_pk_mul_f32 v[46:47], v[46:47], v[64:65] op_sel_hi:[1,0]
	v_add_f32_e32 v19, 0, v24
	v_add_f32_e32 v19, v25, v19
	v_add_f32_e32 v19, v26, v19
	v_add_f32_e32 v19, v27, v19
	v_pk_mul_f32 v[50:51], v[60:61], v[64:65] op_sel_hi:[1,0]
	v_pk_mul_f32 v[52:53], v[56:57], v[64:65] op_sel_hi:[1,0]
	s_waitcnt vmcnt(0)
	v_pk_fma_f32 v[34:35], v[34:35], v[44:45], v[38:39]
	v_pk_fma_f32 v[36:37], v[36:37], v[42:43], v[40:41]
	global_store_dwordx4 v[62:63], v[34:37], off offset:1024
	global_load_dwordx4 v[38:41], v[2:3], off offset:2048
	global_load_dwordx4 v[42:45], v[4:5], off offset:2048
	v_add_f32_e32 v19, v34, v19
	v_add_f32_e32 v19, v35, v19
	v_add_f32_e32 v19, v36, v19
	v_add_f32_e32 v19, v37, v19
	s_waitcnt vmcnt(0)
	v_pk_fma_f32 v[38:39], v[38:39], v[48:49], v[42:43]
	v_pk_fma_f32 v[40:41], v[40:41], v[46:47], v[44:45]
	global_store_dwordx4 v[62:63], v[38:41], off offset:2048
	global_load_dwordx4 v[42:45], v[2:3], off offset:3072
	global_load_dwordx4 v[46:49], v[4:5], off offset:3072
	v_add_f32_e32 v19, v38, v19
	v_add_f32_e32 v19, v39, v19
	v_add_f32_e32 v19, v40, v19
	v_add_f32_e32 v19, v41, v19
	s_waitcnt vmcnt(0)
	v_pk_fma_f32 v[42:43], v[42:43], v[50:51], v[46:47]
	s_nop 0
	v_add_f32_e32 v19, v42, v19
	v_pk_fma_f32 v[44:45], v[44:45], v[52:53], v[48:49]
	v_add_f32_e32 v19, v43, v19
	v_add_f32_e32 v19, v44, v19
	v_add_f32_e32 v19, v45, v19
	v_mov_b32_e32 v21, v19
	s_nop 1
	v_permlane32_swap_b32_e32 v21, v19
	v_mov_b64_e32 v[46:47], s[10:11]
	v_mad_i64_i32 v[50:51], s[26:27], v17, s4, v[46:47]
	s_mov_b64 s[26:27], 0x4000
	s_waitcnt lgkmcnt(0)
	v_add_f32_e32 v19, v19, v21
	v_mov_b32_e32 v21, v19
	s_nop 1
	v_permlane16_swap_b32_e32 v21, v19
	v_lshl_add_u64 v[54:55], v[50:51], 0, s[26:27]
	v_lshl_add_u64 v[46:47], v[54:55], 0, v[0:1]
	global_store_dwordx4 v[62:63], v[42:45], off offset:3072
	s_mov_b64 s[26:27], 0x3000
	s_waitcnt lgkmcnt(0)
	v_add_f32_e32 v19, v19, v21
	s_nop 1
	v_mov_b32_dpp v21, v19 row_ror:8 row_mask:0xf bank_mask:0xf
	global_load_dwordx4 v[46:49], v[46:47], off
	v_lshl_add_u64 v[56:57], v[50:51], 0, s[26:27]
	v_lshl_add_u64 v[50:51], v[56:57], 0, v[0:1]
	global_load_dwordx4 v[50:53], v[50:51], off
	s_waitcnt lgkmcnt(0)
	v_add_f32_e32 v19, v19, v21
	s_nop 1
	v_mov_b32_dpp v21, v19 quad_perm:[3,2,1,0] row_mask:0xf bank_mask:0xf
	s_nop 1
	v_mov_b32_dpp v21, v21 row_half_mirror row_mask:0xf bank_mask:0xf
	s_waitcnt lgkmcnt(0)
	v_add_f32_e32 v17, v19, v21
	s_nop 1
	v_mov_b32_dpp v19, v17 quad_perm:[2,3,0,1] row_mask:0xf bank_mask:0xf
	s_waitcnt lgkmcnt(0)
	v_add_f32_e32 v17, v17, v19
	s_nop 1
	v_mov_b32_dpp v19, v17 quad_perm:[1,0,3,2] row_mask:0xf bank_mask:0xf
	s_waitcnt lgkmcnt(0)
	v_add_f32_e32 v17, v17, v19
	v_mul_f32_e32 v58, 0x3a800000, v17
	v_pk_add_f32 v[24:25], v[24:25], v[58:59] op_sel_hi:[1,0] neg_lo:[0,1] neg_hi:[0,1]
	v_pk_add_f32 v[26:27], v[26:27], v[58:59] op_sel_hi:[1,0] neg_lo:[0,1] neg_hi:[0,1]
	v_pk_add_f32 v[60:61], v[36:37], v[58:59] op_sel_hi:[1,0] neg_lo:[0,1] neg_hi:[0,1]
	v_pk_mul_f32 v[36:37], v[24:25], v[24:25]
	v_pk_add_f32 v[62:63], v[34:35], v[58:59] op_sel_hi:[1,0] neg_lo:[0,1] neg_hi:[0,1]
	v_pk_mul_f32 v[34:35], v[26:27], v[26:27]
	v_add_f32_e32 v17, v36, v37
	v_add_f32_e32 v17, v34, v17
	v_pk_mul_f32 v[64:65], v[62:63], v[62:63]
	v_add_f32_e32 v17, v35, v17
	v_add_f32_e32 v17, v64, v17
	v_pk_add_f32 v[40:41], v[40:41], v[58:59] op_sel_hi:[1,0] neg_lo:[0,1] neg_hi:[0,1]
	v_pk_add_f32 v[38:39], v[38:39], v[58:59] op_sel_hi:[1,0] neg_lo:[0,1] neg_hi:[0,1]
	v_pk_add_f32 v[44:45], v[44:45], v[58:59] op_sel_hi:[1,0] neg_lo:[0,1] neg_hi:[0,1]
	v_pk_add_f32 v[42:43], v[42:43], v[58:59] op_sel_hi:[1,0] neg_lo:[0,1] neg_hi:[0,1]
	v_pk_mul_f32 v[58:59], v[60:61], v[60:61]
	v_add_f32_e32 v17, v65, v17
	v_add_f32_e32 v17, v58, v17
	v_pk_mul_f32 v[68:69], v[38:39], v[38:39]
	v_add_f32_e32 v17, v59, v17
	v_add_f32_e32 v17, v68, v17
	v_pk_mul_f32 v[66:67], v[40:41], v[40:41]
	v_add_f32_e32 v17, v69, v17
	v_add_f32_e32 v17, v66, v17
	v_pk_mul_f32 v[72:73], v[42:43], v[42:43]
	v_add_f32_e32 v17, v67, v17
	v_add_f32_e32 v17, v72, v17
	v_pk_mul_f32 v[70:71], v[44:45], v[44:45]
	v_add_f32_e32 v17, v73, v17
	v_add_f32_e32 v17, v70, v17
	v_add_f32_e32 v17, v71, v17
	v_mov_b32_e32 v19, v17
	s_nop 1
	v_permlane32_swap_b32_e32 v19, v17
	v_lshl_add_u64 v[58:59], v[10:11], 0, v[22:23]
	s_waitcnt lgkmcnt(0)
	v_add_f32_e32 v17, v17, v19
	v_mov_b32_e32 v19, v17
	s_nop 1
	v_permlane16_swap_b32_e32 v19, v17
	s_waitcnt lgkmcnt(0)
	v_add_f32_e32 v17, v17, v19
	s_nop 1
	v_mov_b32_dpp v19, v17 row_ror:8 row_mask:0xf bank_mask:0xf
	s_waitcnt lgkmcnt(0)
	v_add_f32_e32 v17, v17, v19
	s_nop 1
	v_mov_b32_dpp v19, v17 quad_perm:[3,2,1,0] row_mask:0xf bank_mask:0xf
	s_nop 1
	v_mov_b32_dpp v19, v19 row_half_mirror row_mask:0xf bank_mask:0xf
	s_waitcnt lgkmcnt(0)
	v_add_f32_e32 v17, v17, v19
	s_nop 1
	v_mov_b32_dpp v19, v17 quad_perm:[2,3,0,1] row_mask:0xf bank_mask:0xf
	s_waitcnt vmcnt(1)
	v_pk_add_f32 v[36:37], v[46:47], 1.0 op_sel_hi:[1,0]
	v_pk_add_f32 v[34:35], v[48:49], 1.0 op_sel_hi:[1,0]
	s_waitcnt lgkmcnt(0)
	v_add_f32_e32 v19, v17, v19
	s_nop 1
	v_mov_b32_dpp v21, v19 quad_perm:[1,0,3,2] row_mask:0xf bank_mask:0xf
	v_mov_b32_e32 v17, v1
	v_lshl_add_u64 v[22:23], v[54:55], 0, v[16:17]
	s_waitcnt lgkmcnt(0)
	v_add_f32_e32 v19, v19, v21
	v_fmamk_f32 v19, v19, 0x3a800000, v208
	v_mul_f32_e32 v21, 0x4b800000, v19
	v_cmp_gt_f32_e32 vcc, s5, v19
	s_nop 1
	v_cndmask_b32_e32 v19, v19, v21, vcc
	v_rsq_f32_e32 v19, v19
	s_nop 0
	v_mul_f32_e32 v21, 0x45800000, v19
	v_cndmask_b32_e32 v46, v19, v21, vcc
	v_pk_mul_f32 v[24:25], v[24:25], v[46:47] op_sel_hi:[1,0]
	v_pk_mul_f32 v[26:27], v[26:27], v[46:47] op_sel_hi:[1,0]
	s_waitcnt vmcnt(0)
	v_pk_fma_f32 v[24:25], v[36:37], v[24:25], v[50:51]
	v_pk_fma_f32 v[26:27], v[34:35], v[26:27], v[52:53]
	v_cvt_pk_bf16_f32 v24, v24, v25
	v_cvt_pk_bf16_f32 v25, v26, v27
	global_store_dwordx2 v[58:59], v[24:25], off
	global_load_dwordx4 v[22:25], v[22:23], off
	v_lshl_add_u64 v[26:27], v[56:57], 0, v[16:17]
	global_load_dwordx4 v[34:37], v[26:27], off
	v_pk_mul_f32 v[48:49], v[62:63], v[46:47] op_sel_hi:[1,0]
	v_pk_mul_f32 v[50:51], v[60:61], v[46:47] op_sel_hi:[1,0]
	v_mov_b32_e32 v19, v1
	v_lshl_add_u64 v[26:27], v[54:55], 0, v[18:19]
	v_pk_mul_f32 v[38:39], v[38:39], v[46:47] op_sel_hi:[1,0]
	v_pk_mul_f32 v[40:41], v[40:41], v[46:47] op_sel_hi:[1,0]
	v_mov_b32_e32 v21, v1
	v_cmp_le_i32_e32 vcc, s1, v12
	s_or_b64 s[8:9], vcc, s[8:9]
	s_waitcnt vmcnt(1)
	v_pk_add_f32 v[22:23], v[22:23], 1.0 op_sel_hi:[1,0]
	v_pk_add_f32 v[24:25], v[24:25], 1.0 op_sel_hi:[1,0]
	s_waitcnt vmcnt(0)
	v_pk_fma_f32 v[22:23], v[22:23], v[48:49], v[34:35]
	v_pk_fma_f32 v[24:25], v[24:25], v[50:51], v[36:37]
	v_cvt_pk_bf16_f32 v22, v22, v23
	v_cvt_pk_bf16_f32 v23, v24, v25
	global_store_dwordx2 v[58:59], v[22:23], off offset:512
	global_load_dwordx4 v[22:25], v[26:27], off
	v_lshl_add_u64 v[26:27], v[56:57], 0, v[18:19]
	global_load_dwordx4 v[34:37], v[26:27], off
	v_lshl_add_u64 v[26:27], v[54:55], 0, v[20:21]
	s_waitcnt vmcnt(1)
	v_pk_add_f32 v[22:23], v[22:23], 1.0 op_sel_hi:[1,0]
	v_pk_add_f32 v[24:25], v[24:25], 1.0 op_sel_hi:[1,0]
	s_waitcnt vmcnt(0)
	v_pk_fma_f32 v[22:23], v[22:23], v[38:39], v[34:35]
	v_pk_fma_f32 v[24:25], v[24:25], v[40:41], v[36:37]
	v_cvt_pk_bf16_f32 v22, v22, v23
	v_cvt_pk_bf16_f32 v23, v24, v25
	global_store_dwordx2 v[58:59], v[22:23], off offset:1024
	global_load_dwordx4 v[22:25], v[26:27], off
	v_lshl_add_u64 v[26:27], v[56:57], 0, v[20:21]
	global_load_dwordx4 v[34:37], v[26:27], off
	v_pk_mul_f32 v[26:27], v[42:43], v[46:47] op_sel_hi:[1,0]
	v_pk_mul_f32 v[38:39], v[44:45], v[46:47] op_sel_hi:[1,0]
	s_waitcnt vmcnt(1)
	v_pk_add_f32 v[22:23], v[22:23], 1.0 op_sel_hi:[1,0]
	v_pk_add_f32 v[24:25], v[24:25], 1.0 op_sel_hi:[1,0]
	s_waitcnt vmcnt(0)
	v_pk_fma_f32 v[22:23], v[22:23], v[26:27], v[34:35]
	v_pk_fma_f32 v[24:25], v[24:25], v[38:39], v[36:37]
	v_cvt_pk_bf16_f32 v22, v22, v23
	v_cvt_pk_bf16_f32 v23, v24, v25
	global_store_dwordx2 v[58:59], v[22:23], off offset:1536
	s_andn2_b64 exec, exec, s[8:9]
	s_cbranch_execz .LBB0_268

.LBB0_324:
	s_or_b64 exec, exec, s[22:23]
	v_and_b32_e32 v18, 0xffff0000, v24
	v_lshlrev_b32_e32 v19, 16, v24
	v_and_b32_e32 v20, 0xffff0000, v28
	v_lshlrev_b32_e32 v21, 16, v28
	v_pk_add_f32 v[52:53], v[18:19], v[20:21]
	v_and_b32_e32 v18, 0xffff0000, v25
	v_lshlrev_b32_e32 v19, 16, v25
	v_and_b32_e32 v20, 0xffff0000, v29
	v_lshlrev_b32_e32 v21, 16, v29
	v_pk_add_f32 v[54:55], v[18:19], v[20:21]
	v_and_b32_e32 v18, 0xffff0000, v49
	v_lshlrev_b32_e32 v19, 16, v49
	v_and_b32_e32 v20, 0xffff0000, v51
	v_lshlrev_b32_e32 v21, 16, v51
	v_pk_add_f32 v[60:61], v[18:19], v[20:21]
	v_lshlrev_b32_e32 v18, 16, v23
	v_and_b32_e32 v19, 0xffff0000, v23
	v_lshlrev_b32_e32 v20, 16, v27
	v_and_b32_e32 v21, 0xffff0000, v27
	v_pk_add_f32 v[56:57], v[18:19], v[20:21]
	v_lshlrev_b32_e32 v19, 16, v15
	v_and_b32_e32 v15, 0xffff0000, v15
	v_mul_f32_e32 v18, 0xbfb8aa3b, v19
	v_cndmask_b32_e64 v21, v15, 1.0, s[40:41]
	v_mul_f32_e32 v15, 0xbfb8aa3b, v15
	v_exp_f32_e32 v18, v18
	v_cndmask_b32_e64 v20, v19, 1.0, s[40:41]
	v_exp_f32_e32 v19, v15
	v_lshlrev_b32_e32 v58, 16, v22
	v_and_b32_e32 v59, 0xffff0000, v22
	v_lshlrev_b32_e32 v22, 16, v26
	v_pk_add_f32 v[18:19], v[18:19], 1.0 op_sel_hi:[1,0]
	v_lshl_add_u64 v[24:25], v[34:35], 0, v[0:1]
	v_rcp_f32_e32 v15, v19
	v_lshl_add_u64 v[34:35], v[34:35], 0, s[12:13]
	v_lshl_add_u64 v[36:37], v[36:37], 0, s[10:11]
	v_lshl_add_u64 v[38:39], v[38:39], 0, s[14:15]
	v_mul_f32_e32 v29, v21, v15
	v_rcp_f32_e32 v15, v18
	v_and_b32_e32 v23, 0xffff0000, v26
	v_pk_add_f32 v[22:23], v[58:59], v[22:23]
	v_mul_f32_e32 v28, v20, v15
	v_add_f32_e32 v15, 0, v22
	v_add_f32_e32 v26, v23, v15
	v_lshlrev_b32_e32 v15, 16, v14
	v_and_b32_e32 v27, 0xffff0000, v14
	v_mul_f32_e32 v14, 0xbfb8aa3b, v15
	v_cndmask_b32_e64 v31, v15, 1.0, s[40:41]
	v_mul_f32_e32 v15, 0xbfb8aa3b, v27
	v_exp_f32_e32 v14, v14
	v_exp_f32_e32 v15, v15
	v_cndmask_b32_e64 v49, v27, 1.0, s[40:41]
	v_add_f32_e32 v26, v56, v26
	v_add_f32_e32 v26, v57, v26
	v_pk_add_f32 v[14:15], v[14:15], 1.0 op_sel_hi:[1,0]
	v_add_f32_e32 v26, v53, v26
	v_rcp_f32_e32 v27, v15
	v_add_f32_e32 v26, v52, v26
	v_add_f32_e32 v26, v55, v26
	v_mul_f32_e32 v15, v49, v27
	v_rcp_f32_e32 v27, v14
	s_nop 0
	v_mul_f32_e32 v14, v31, v27
	v_add_f32_e32 v31, v54, v26
	v_and_b32_e32 v26, 0xffff0000, v48
	v_lshlrev_b32_e32 v27, 16, v48
	v_and_b32_e32 v48, 0xffff0000, v50
	v_lshlrev_b32_e32 v49, 16, v50
	v_pk_add_f32 v[26:27], v[26:27], v[48:49]
	s_nop 0
	v_add_f32_e32 v31, v27, v31
	v_add_f32_e32 v31, v26, v31
	v_add_f32_e32 v31, v61, v31
	v_add_f32_e32 v31, v60, v31
	s_nop 1
	v_mov_b32_dpp v48, v31 quad_perm:[1,0,3,2] row_mask:0xf bank_mask:0xf
	s_waitcnt lgkmcnt(0)
	v_add_f32_e32 v31, v31, v48
	s_nop 1
	v_mov_b32_dpp v48, v31 quad_perm:[2,3,0,1] row_mask:0xf bank_mask:0xf
	s_waitcnt lgkmcnt(0)
	v_add_f32_e32 v31, v31, v48
	s_nop 1
	v_mov_b32_dpp v48, v31 quad_perm:[3,2,1,0] row_mask:0xf bank_mask:0xf
	s_nop 1
	v_mov_b32_dpp v48, v48 row_half_mirror row_mask:0xf bank_mask:0xf
	s_waitcnt lgkmcnt(0)
	v_add_f32_e32 v31, v31, v48
	v_mul_f32_e32 v70, 0x3c2aaaab, v31
	v_lshlrev_b32_e32 v31, 16, v17
	v_and_b32_e32 v17, 0xffff0000, v17
	v_pk_add_f32 v[48:49], v[54:55], v[70:71] op_sel_hi:[1,0] neg_lo:[0,1] neg_hi:[0,1]
	v_mul_f32_e32 v50, 0xbfb8aa3b, v31
	v_cndmask_b32_e64 v54, v17, 1.0, s[40:41]
	v_mul_f32_e32 v17, 0xbfb8aa3b, v17
	v_exp_f32_e32 v50, v50
	v_exp_f32_e32 v51, v17
	v_pk_add_f32 v[58:59], v[22:23], v[70:71] op_sel_hi:[1,0] neg_lo:[0,1] neg_hi:[0,1]
	v_pk_add_f32 v[56:57], v[56:57], v[70:71] op_sel_hi:[1,0] neg_lo:[0,1] neg_hi:[0,1]
	v_pk_add_f32 v[26:27], v[26:27], v[70:71] op_sel_hi:[1,0] neg_lo:[0,1] neg_hi:[0,1]
	v_pk_add_f32 v[50:51], v[50:51], 1.0 op_sel_hi:[1,0]
	v_pk_add_f32 v[22:23], v[60:61], v[70:71] op_sel_hi:[1,0] neg_lo:[0,1] neg_hi:[0,1]
	v_rcp_f32_e32 v17, v51
	v_cndmask_b32_e64 v31, v31, 1.0, s[40:41]
	v_pk_mul_f32 v[64:65], v[58:59], v[58:59]
	v_pk_mul_f32 v[66:67], v[56:57], v[56:57]
	v_mul_f32_e32 v51, v54, v17
	v_rcp_f32_e32 v17, v50
	v_pk_mul_f32 v[68:69], v[48:49], v[48:49]
	v_pk_mul_f32 v[62:63], v[26:27], v[26:27]
	v_pk_mul_f32 v[60:61], v[22:23], v[22:23]
	v_mul_f32_e32 v50, v31, v17
	v_lshlrev_b32_e32 v17, 16, v16
	v_and_b32_e32 v31, 0xffff0000, v16
	v_mul_f32_e32 v16, 0xbfb8aa3b, v17
	v_cndmask_b32_e64 v54, v17, 1.0, s[40:41]
	v_mul_f32_e32 v17, 0xbfb8aa3b, v31
	v_exp_f32_e32 v16, v16
	v_exp_f32_e32 v17, v17
	v_cndmask_b32_e64 v55, v31, 1.0, s[40:41]
	v_pk_add_f32 v[70:71], v[52:53], v[70:71] op_sel_hi:[1,0] neg_lo:[0,1] neg_hi:[0,1]
	v_pk_add_f32 v[16:17], v[16:17], 1.0 op_sel_hi:[1,0]
	s_nop 0
	v_rcp_f32_e32 v31, v17
	v_pk_mul_f32 v[52:53], v[70:71], v[70:71]
	v_mul_f32_e32 v55, v55, v31
	v_rcp_f32_e32 v17, v16
	s_nop 0
	v_mul_f32_e32 v54, v54, v17
	v_add_f32_e32 v16, v64, v65
	v_add_f32_e32 v16, v66, v16
	v_add_f32_e32 v16, v67, v16
	v_add_f32_e32 v16, v53, v16
	v_add_f32_e32 v16, v52, v16
	v_add_f32_e32 v16, v69, v16
	v_add_f32_e32 v16, v68, v16
	v_add_f32_e32 v16, v63, v16
	v_add_f32_e32 v16, v62, v16
	v_add_f32_e32 v16, v61, v16
	v_add_f32_e32 v16, v60, v16
	s_nop 1
	v_mov_b32_dpp v17, v16 quad_perm:[1,0,3,2] row_mask:0xf bank_mask:0xf
	s_waitcnt lgkmcnt(0)
	v_add_f32_e32 v16, v16, v17
	s_nop 1
	v_mov_b32_dpp v17, v16 quad_perm:[2,3,0,1] row_mask:0xf bank_mask:0xf
	s_waitcnt lgkmcnt(0)
	v_add_f32_e32 v16, v16, v17
	s_nop 1
	v_mov_b32_dpp v17, v16 quad_perm:[3,2,1,0] row_mask:0xf bank_mask:0xf
	s_nop 1
	v_mov_b32_dpp v17, v17 row_half_mirror row_mask:0xf bank_mask:0xf
	s_waitcnt lgkmcnt(0)
	v_add_f32_e32 v16, v16, v17
	v_fmamk_f32 v16, v16, 0x3c2aaaab, v208
	v_cmp_gt_f32_e32 vcc, s5, v16
	v_mul_f32_e32 v17, 0x4b800000, v16
	s_nop 0
	v_cndmask_b32_e32 v16, v16, v17, vcc
	v_rsq_f32_e32 v16, v16
	s_nop 0
	v_mul_f32_e32 v17, 0x45800000, v16
	v_cndmask_b32_e32 v52, v16, v17, vcc
	v_pk_mul_f32 v[16:17], v[58:59], v[52:53] op_sel_hi:[1,0]
	v_mul_f32_e32 v23, v23, v52
	v_pk_mul_f32 v[16:17], v[80:81], v[16:17]
	v_pk_mul_f32 v[18:19], v[70:71], v[52:53] op_sel_hi:[1,0]
	v_pk_mul_f32 v[14:15], v[14:15], v[16:17]
	v_pk_mul_f32 v[16:17], v[56:57], v[52:53] op_sel_hi:[1,0]
	v_cvt_pk_bf16_f32 v14, v14, v15
	v_pk_mul_f32 v[16:17], v[82:83], v[16:17]
	v_and_b32_e32 v20, 0xffff0000, v45
	v_pk_mul_f32 v[16:17], v[28:29], v[16:17]
	s_nop 0
	v_cvt_pk_bf16_f32 v15, v16, v17
	global_store_dwordx2 v[24:25], v[14:15], off offset:512
	v_pk_mul_f32 v[14:15], v[84:85], v[18:19] op_sel:[0,1] op_sel_hi:[1,0]
	v_pk_mul_f32 v[18:19], v[48:49], v[52:53] op_sel_hi:[1,0]
	v_pk_mul_f32 v[14:15], v[54:55], v[14:15]
	v_pk_mul_f32 v[16:17], v[86:87], v[18:19] op_sel:[0,1] op_sel_hi:[1,0]
	v_cvt_pk_bf16_f32 v14, v14, v15
	v_pk_mul_f32 v[16:17], v[50:51], v[16:17]
	v_and_b32_e32 v18, 0xffff0000, v44
	v_cvt_pk_bf16_f32 v15, v16, v17
	global_store_dwordx2 v[24:25], v[14:15], off offset:520
	v_lshlrev_b32_e32 v14, 16, v44
	v_cndmask_b32_e64 v15, v14, 1.0, s[40:41]
	v_mul_f32_e32 v14, 0xbfb8aa3b, v14
	v_exp_f32_e32 v14, v14
	v_lshlrev_b32_e32 v19, 16, v45
	v_add_f32_e32 v14, 1.0, v14
	v_rcp_f32_e32 v16, v14
	s_nop 0
	v_mul_f32_e32 v21, v15, v16
	v_cndmask_b32_e64 v28, v18, 1.0, s[40:41]
	v_mul_f32_e32 v18, 0xbfb8aa3b, v18
	v_exp_f32_e32 v18, v18
	v_mul_f32_e32 v16, v90, v23
	v_add_f32_e32 v18, 1.0, v18
	v_rcp_f32_e32 v29, v18
	s_nop 0
	v_mul_f32_e32 v18, v28, v29
	v_cndmask_b32_e64 v28, v19, 1.0, s[40:41]
	v_mul_f32_e32 v19, 0xbfb8aa3b, v19
	v_exp_f32_e32 v19, v19
	s_nop 0
	v_add_f32_e32 v19, 1.0, v19
	v_rcp_f32_e32 v29, v19
	s_nop 0
	v_mul_f32_e32 v19, v28, v29
	v_cndmask_b32_e64 v28, v20, 1.0, s[40:41]
	v_mul_f32_e32 v20, 0xbfb8aa3b, v20
	v_exp_f32_e32 v20, v20
	v_mul_f32_e32 v16, v19, v16
	v_mul_f32_e32 v19, v26, v52
	v_mul_f32_e32 v15, v89, v19
	v_add_f32_e32 v20, 1.0, v20
	v_rcp_f32_e32 v29, v20
	v_mul_f32_e32 v15, v18, v15
	v_mul_f32_e32 v18, v27, v52
	v_mul_f32_e32 v14, v88, v18
	v_mul_f32_e32 v18, v22, v52
	v_mul_f32_e32 v20, v28, v29
	v_mul_f32_e32 v17, v91, v18
	v_mul_f32_e32 v14, v21, v14
	v_mul_f32_e32 v17, v20, v17
	v_cvt_pk_bf16_f32 v14, v14, v15
	v_cvt_pk_bf16_f32 v15, v16, v17
	global_store_dwordx2 v[24:25], v[14:15], off offset:528
	s_waitcnt vmcnt(3)
	v_mov_b64_e32 v[50:51], v[42:43]
	v_mov_b64_e32 v[22:23], v[2:3]
	v_mov_b64_e32 v[24:25], v[4:5]
	v_mov_b64_e32 v[48:49], v[40:41]
	v_mov_b64_e32 v[26:27], v[6:7]
	v_mov_b64_e32 v[28:29], v[8:9]
	v_mov_b64_e32 v[14:15], v[10:11]
	v_mov_b64_e32 v[16:17], v[12:13]
	v_mov_b64_e32 v[44:45], v[46:47]
	s_andn2_b64 exec, exec, s[18:19]
	s_cbranch_execz .LBB0_327

.LBB0_541:
	s_or_b64 exec, exec, s[10:11]
	s_waitcnt lgkmcnt(0)
	s_barrier
	ds_read_b96 v[54:56], v71 offset:46720
	s_and_b64 vcc, exec, s[60:61]
	s_mov_b64 s[10:11], -1
	s_cbranch_vccnz .LBB0_545
	ds_read_b128 v[46:49], v168
	ds_read_b128 v[50:53], v168 offset:16
	ds_read_b128 v[198:201], v168 offset:32
	ds_read_b128 v[202:205], v183 offset:46336
	ds_read_b128 v[234:237], v183 offset:46352
	ds_read_b128 v[238:241], v183 offset:46368
	ds_read_b128 v[242:245], v183 offset:46384
	s_waitcnt lgkmcnt(6)
	v_lshlrev_b32_e32 v93, 16, v46
	v_and_b32_e32 v46, 0xffff0000, v46
	s_waitcnt lgkmcnt(3)
	v_mul_f32_e32 v46, v203, v46
	v_fmac_f32_e32 v46, v202, v93
	v_lshlrev_b32_e32 v93, 16, v47
	v_fmac_f32_e32 v46, v204, v93
	v_and_b32_e32 v47, 0xffff0000, v47
	v_fmac_f32_e32 v46, v205, v47
	v_lshlrev_b32_e32 v47, 16, v48
	s_waitcnt lgkmcnt(2)
	v_fmac_f32_e32 v46, v234, v47
	v_and_b32_e32 v47, 0xffff0000, v48
	v_fmac_f32_e32 v46, v235, v47
	v_lshlrev_b32_e32 v47, 16, v49
	v_fmac_f32_e32 v46, v236, v47
	v_and_b32_e32 v47, 0xffff0000, v49
	v_fmac_f32_e32 v46, v237, v47
	v_and_b32_e32 v47, 0xffff0000, v50
	v_add_f32_e32 v93, 0, v46
	v_lshlrev_b32_e32 v46, 16, v50
	s_waitcnt lgkmcnt(1)
	v_mul_f32_e32 v50, v239, v47
	v_fmac_f32_e32 v50, v238, v46
	v_lshlrev_b32_e32 v46, 16, v51
	v_fmac_f32_e32 v50, v240, v46
	v_and_b32_e32 v46, 0xffff0000, v51
	v_fmac_f32_e32 v50, v241, v46
	v_lshlrev_b32_e32 v51, 16, v52
	ds_read_b128 v[46:49], v183 offset:46400
	s_waitcnt lgkmcnt(1)
	v_fmac_f32_e32 v50, v242, v51
	v_and_b32_e32 v51, 0xffff0000, v52
	v_fmac_f32_e32 v50, v243, v51
	v_lshlrev_b32_e32 v51, 16, v53
	v_fmac_f32_e32 v50, v244, v51
	v_and_b32_e32 v51, 0xffff0000, v53
	v_fmac_f32_e32 v50, v245, v51
	v_add_f32_e32 v93, v93, v50
	ds_read_b128 v[50:53], v183 offset:46416
	v_and_b32_e32 v197, 0xffff0000, v198
	v_lshlrev_b32_e32 v95, 16, v198
	s_waitcnt lgkmcnt(1)
	v_mul_f32_e32 v47, v47, v197
	v_fmac_f32_e32 v47, v46, v95
	v_lshlrev_b32_e32 v46, 16, v199
	v_fmac_f32_e32 v47, v48, v46
	v_and_b32_e32 v46, 0xffff0000, v199
	v_fmac_f32_e32 v47, v49, v46
	v_lshlrev_b32_e32 v46, 16, v200
	s_waitcnt lgkmcnt(0)
	v_fmac_f32_e32 v47, v50, v46
	v_and_b32_e32 v46, 0xffff0000, v200
	v_fmac_f32_e32 v47, v51, v46
	v_lshlrev_b32_e32 v46, 16, v201
	v_fmac_f32_e32 v47, v52, v46
	v_and_b32_e32 v46, 0xffff0000, v201
	v_fmac_f32_e32 v47, v53, v46
	v_and_b32_e32 v48, 64, v209
	v_add_f32_e32 v46, v93, v47
	v_xor_b32_e32 v47, 1, v209
	v_add_u32_e32 v48, 64, v48
	v_cmp_lt_i32_e32 vcc, v47, v48
	s_nop 1
	v_cndmask_b32_e32 v47, v209, v47, vcc
	v_lshlrev_b32_e32 v47, 2, v47
	s_nop 1
	v_mov_b32_dpp v47, v46 quad_perm:[1,0,3,2] row_mask:0xf bank_mask:0xf
	s_waitcnt lgkmcnt(0)
	v_add_f32_e32 v46, v46, v47
	v_xor_b32_e32 v47, 2, v209
	v_cmp_lt_i32_e32 vcc, v47, v48
	s_nop 1
	v_cndmask_b32_e32 v47, v209, v47, vcc
	v_lshlrev_b32_e32 v47, 2, v47
	s_nop 1
	v_mov_b32_dpp v47, v46 quad_perm:[2,3,0,1] row_mask:0xf bank_mask:0xf
	s_and_saveexec_b64 s[10:11], s[56:57]
	s_cbranch_execz .LBB0_544
	s_waitcnt lgkmcnt(0)
	v_add_f32_e32 v46, v46, v47
	ds_write_b32 v184, v46 offset:46080

.LBB0_630:
	v_cndmask_b32_e64 v0, v130, v126, s[70:71]
	s_movk_i32 s1, 0x68
	v_mad_u32_u24 v0, v0, s1, v100
	v_lshl_add_u32 v0, v0, 1, v124
	s_waitcnt lgkmcnt(0)
	s_barrier
	ds_write_b128 v0, v[4:7]
	ds_write_b128 v0, v[8:11] offset:13312
	ds_write_b128 v0, v[16:19] offset:26624
	v_cndmask_b32_e64 v0, v131, v128, s[70:71]
	v_mad_u32_u24 v0, v0, s1, v102
	v_lshl_add_u32 v0, v0, 1, v124
	ds_write_b128 v0, v[12:15]
	ds_write_b128 v0, v[20:23] offset:13312
	ds_write_b128 v0, v[28:31] offset:26624
	v_cndmask_b32_e64 v0, v132, v129, s[70:71]
	v_mad_u32_u24 v0, v0, s1, v104
	v_lshl_add_u32 v0, v0, 1, v124
	ds_write_b128 v0, v[24:27]
	ds_write_b128 v0, v[32:35] offset:13312
	ds_write_b128 v0, v[36:39] offset:26624
	s_and_saveexec_b64 s[96:97], s[42:43]
	s_cbranch_execz .LBB0_633
	s_lshl_b32 s1, s76, 2
	v_or_b32_e32 v2, s1, v169
	v_ashrrev_i32_e32 v3, 31, v2
	v_lshlrev_b64 v[2:3], 2, v[2:3]
	v_lshl_add_u64 v[76:77], s[90:91], 0, v[2:3]
	global_load_dword v0, v[76:77], off
	v_lshl_add_u64 v[2:3], s[88:89], 0, v[2:3]
	global_load_dword v2, v[2:3], off
	v_cndmask_b32_e64 v78, v101, v117, s[70:71]
	v_lshlrev_b32_e32 v78, 16, v78
	s_mov_b64 vcc, s[70:71]
	v_and_b32_e32 v79, 64, v209
	v_add_u32_e32 v80, -1, v209
	v_add_u32_e32 v81, -2, v209
	v_cndmask_b32_sdwa v76, v105, v103, vcc dst_sel:WORD_1 dst_unused:UNUSED_PAD src0_sel:DWORD src1_sel:DWORD
	v_cmp_lt_i32_e32 vcc, v80, v79
	v_add_u32_e32 v82, -4, v209
	v_add_u32_e32 v83, -8, v209
	v_cndmask_b32_e32 v80, v80, v209, vcc
	v_cmp_lt_i32_e32 vcc, v81, v79
	v_add_u32_e32 v84, -16, v209
	v_subrev_u32_e32 v85, 32, v209
	v_cndmask_b32_e32 v81, v81, v209, vcc
	v_cmp_lt_i32_e32 vcc, v82, v79
	v_cndmask_b32_e64 v77, v133, v123, s[70:71]
	v_xor_b32_e32 v87, 32, v209
	v_cndmask_b32_e32 v82, v82, v209, vcc
	v_xor_b32_e32 v88, 16, v209
	v_xor_b32_e32 v89, 8, v209
	v_xor_b32_e32 v90, 4, v209
	v_xor_b32_e32 v3, 2, v209
	v_lshl_or_b32 v86, v209, 2, v224
	v_xor_b32_e32 v91, 1, v209
	s_lshl_b64 s[38:39], s[76:77], 2
	s_waitcnt vmcnt(1)
	v_add_f32_e32 v0, v0, v78
	v_mul_f32_e64 v78, |v0|, s36
	v_exp_f32_e32 v78, v78
	v_min_f32_e32 v0, 0, v0
	v_add_f32_e32 v78, 1.0, v78
	v_cmp_gt_f32_e32 vcc, s5, v78
	s_nop 1
	v_cndmask_b32_e64 v92, 0, 32, vcc
	v_ldexp_f32 v78, v78, v92
	v_log_f32_e32 v78, v78
	v_lshlrev_b32_e32 v92, 2, v80
	v_cndmask_b32_e32 v80, 0, v223, vcc
	v_mul_f32_e32 v93, 0x3f317217, v78
	v_fma_f32 v93, v78, s75, -v93
	v_fmac_f32_e32 v93, 0x3377d1cf, v78
	v_fmac_f32_e32 v93, 0x3f317217, v78
	v_cmp_lt_f32_e64 vcc, |v78|, s33
	s_nop 1
	v_cndmask_b32_e32 v78, v78, v93, vcc
	v_sub_f32_e32 v78, v78, v80
	v_sub_f32_e32 v0, v0, v78
	ds_bpermute_b32 v78, v92, v0
	v_lshlrev_b32_e32 v93, 2, v81
	v_cmp_lt_i32_e32 vcc, v83, v79
	v_or_b32_e32 v80, v77, v171
	s_waitcnt lgkmcnt(0)
	v_add_f32_e32 v78, v0, v78
	v_cndmask_b32_e64 v0, v78, v0, s[44:45]
	ds_bpermute_b32 v78, v93, v0
	v_cndmask_b32_e32 v83, v83, v209, vcc
	v_cmp_lt_i32_e32 vcc, v84, v79
	v_lshlrev_b32_e32 v94, 2, v83
	s_waitcnt lgkmcnt(0)
	v_add_f32_e32 v78, v0, v78
	v_cndmask_b32_e32 v84, v84, v209, vcc
	v_cmp_lt_i32_e32 vcc, v85, v79
	v_cndmask_b32_e64 v0, v78, v0, s[46:47]
	v_lshlrev_b32_e32 v95, 2, v84
	v_cndmask_b32_e32 v81, v85, v209, vcc
	v_lshlrev_b32_e32 v85, 2, v82
	ds_bpermute_b32 v78, v85, v0
	v_add_u32_e32 v79, 64, v79
	v_lshlrev_b32_e32 v96, 2, v81
	v_cmp_lt_i32_e32 vcc, v87, v79
	v_ashrrev_i32_e32 v81, 31, v80
	s_waitcnt lgkmcnt(0)
	v_add_f32_e32 v77, v0, v78
	v_cndmask_b32_e64 v0, v77, v0, s[48:49]
	ds_bpermute_b32 v77, v94, v0
	v_cndmask_b32_e32 v78, v209, v87, vcc
	v_cmp_lt_i32_e32 vcc, v88, v79
	v_lshlrev_b64 v[80:81], 3, v[80:81]
	v_or3_b32 v81, v81, s39, 0
	s_waitcnt lgkmcnt(0)
	v_add_f32_e32 v77, v0, v77
	v_cndmask_b32_e64 v0, v77, v0, s[50:51]
	ds_bpermute_b32 v77, v95, v0
	v_cndmask_b32_e32 v82, v209, v88, vcc
	v_cmp_lt_i32_e32 vcc, v89, v79
	v_or3_b32 v80, v80, s38, v116
	s_waitcnt lgkmcnt(0)
	v_add_f32_e32 v77, v0, v77
	v_cndmask_b32_e64 v0, v77, v0, s[52:53]
	ds_bpermute_b32 v77, v96, v0
	v_cndmask_b32_e32 v83, v209, v89, vcc
	v_cmp_lt_i32_e32 vcc, v90, v79
	v_lshlrev_b32_e32 v89, 2, v82
	s_nop 0
	v_cndmask_b32_e32 v84, v209, v90, vcc
	v_cmp_lt_i32_e32 vcc, v3, v79
	v_lshlrev_b32_e32 v90, 2, v83
	s_nop 0
	v_cndmask_b32_e32 v87, v209, v3, vcc
	s_waitcnt lgkmcnt(0)
	v_add_f32_e32 v3, v0, v77
	v_cndmask_b32_e64 v3, v3, v0, s[54:55]
	ds_bpermute_b32 v77, v86, v3
	v_cmp_lt_i32_e32 vcc, v91, v79
	v_lshlrev_b32_e32 v86, 2, v78
	s_waitcnt vmcnt(0) lgkmcnt(0)
	v_pk_add_f32 v[78:79], v[2:3], v[76:77]
	v_sub_f32_e32 v0, v77, v3
	v_pk_add_f32 v[82:83], v[78:79], v[0:1] op_sel_hi:[1,0]
	v_sub_f32_e32 v79, v78, v3
	ds_bpermute_b32 v0, v86, v82
	ds_bpermute_b32 v2, v92, v79
	v_cndmask_b32_e32 v88, v209, v91, vcc
	v_lshlrev_b32_e32 v91, 2, v84
	v_lshlrev_b32_e32 v76, 2, v87
	s_waitcnt lgkmcnt(1)
	v_max_f32_e32 v0, v0, v0
	s_waitcnt lgkmcnt(0)
	v_max_f32_e32 v2, v2, v2
	v_max_f32_e32 v0, v82, v0
	v_max_f32_e32 v2, v79, v2
	ds_bpermute_b32 v78, v89, v0
	v_cndmask_b32_e64 v2, v2, v79, s[44:45]
	ds_bpermute_b32 v84, v93, v2
	v_lshlrev_b32_e32 v83, 2, v88
	s_waitcnt lgkmcnt(1)
	v_max_f32_e32 v78, v78, v78
	v_max_f32_e32 v0, v0, v78
	s_waitcnt lgkmcnt(0)
	v_max_f32_e32 v78, v84, v84
	v_max_f32_e32 v78, v2, v78
	s_nop 1
	v_mov_b32_dpp v86, v0 row_ror:8 row_mask:0xf bank_mask:0xf
	v_cndmask_b32_e64 v2, v78, v2, s[46:47]
	ds_bpermute_b32 v78, v85, v2
	v_lshl_add_u64 v[84:85], v[80:81], 4, s[12:13]
	s_waitcnt lgkmcnt(1)
	v_max_f32_e32 v80, v86, v86
	v_max_f32_e32 v0, v0, v80
	s_waitcnt lgkmcnt(0)
	v_max_f32_e32 v78, v78, v78
	s_nop 1
	v_mov_b32_dpp v80, v0 quad_perm:[3,2,1,0] row_mask:0xf bank_mask:0xf
	s_nop 1
	v_mov_b32_dpp v80, v80 row_half_mirror row_mask:0xf bank_mask:0xf
	v_max_f32_e32 v78, v2, v78
	v_cndmask_b32_e64 v2, v78, v2, s[48:49]
	ds_bpermute_b32 v81, v94, v2
	v_mov_b32_e32 v78, v3
	s_waitcnt lgkmcnt(1)
	v_max_f32_e32 v3, v80, v80
	v_max_f32_e32 v0, v0, v3
	s_nop 1
	v_mov_b32_dpp v3, v0 quad_perm:[2,3,0,1] row_mask:0xf bank_mask:0xf
	s_waitcnt lgkmcnt(1)
	v_max_f32_e32 v76, v81, v81
	v_max_f32_e32 v76, v2, v76
	v_cndmask_b32_e64 v2, v76, v2, s[50:51]
	ds_bpermute_b32 v76, v95, v2
	s_waitcnt lgkmcnt(1)
	v_max_f32_e32 v3, v3, v3
	v_max_f32_e32 v0, v0, v3
	s_nop 1
	v_mov_b32_dpp v3, v0 quad_perm:[1,0,3,2] row_mask:0xf bank_mask:0xf
	v_mov_b32_e32 v81, v82
	s_waitcnt lgkmcnt(1)
	v_max_f32_e32 v76, v76, v76
	v_max_f32_e32 v76, v2, v76
	v_cndmask_b32_e64 v2, v76, v2, s[52:53]
	ds_bpermute_b32 v76, v96, v2
	s_waitcnt lgkmcnt(1)
	v_max_f32_e32 v3, v3, v3
	v_max_f32_e32 v3, v0, v3
	v_sub_f32_e32 v0, v82, v3
	v_mul_f32_e32 v0, 0x3fb8aa3b, v0
	v_max_f32_e32 v80, v2, v2
	v_exp_f32_e32 v0, v0
	s_waitcnt lgkmcnt(0)
	v_max_f32_e32 v76, v76, v76
	v_max_f32_e32 v76, v80, v76
	v_cndmask_b32_e64 v80, v76, v2, s[54:55]
	global_store_dwordx4 v[84:85], v[78:81], off
	ds_write2st64_b32 v134, v79, v80 offset0:192 offset1:193
	ds_write_b32 v134, v0 offset:49664
	s_and_b64 exec, exec, s[44:45]
	s_cbranch_execz .LBB0_633
	v_or_b32_e32 v0, s1, v172
	v_lshlrev_b32_e32 v78, 1, v0
	v_ashrrev_i32_e32 v79, 31, v78
	v_lshl_add_u64 v[78:79], v[78:79], 2, s[22:23]
	v_mov_b32_e32 v2, v77
	global_store_dwordx2 v[78:79], v[2:3], off

.LBB0_651:
	s_or_b64 exec, exec, s[38:39]
	v_add_u32_e32 v96, 0xc000, v142
	ds_read_b128 v[80:83], v138 offset:49408
	ds_read2_b32 v[2:3], v96 offset1:16
	s_waitcnt lgkmcnt(0)
	v_sub_f32_e32 v0, v2, v80
	v_mul_f32_e32 v0, 0x3fb8aa3b, v0
	v_exp_f32_e32 v0, v0
	s_nop 0
	v_mul_f32_e32 v0, v92, v0
	v_cndmask_b32_e64 v0, v0, 0, s[60:61]
	v_add_f32_e32 v97, 0, v0
	v_cvt_pk_bf16_f32 v0, v0, s0
	ds_write_b16 v143, v0 offset:39936
	v_sub_f32_e32 v0, v2, v81
	v_mul_f32_e32 v0, 0x3fb8aa3b, v0
	v_exp_f32_e32 v0, v0
	s_nop 0
	v_mul_f32_e32 v0, v93, v0
	v_cndmask_b32_e64 v0, v0, 0, s[62:63]
	v_cvt_pk_bf16_f32 v92, v0, s0
	ds_write_b16 v144, v92 offset:39936
	v_sub_f32_e32 v92, v2, v82
	v_mul_f32_e32 v92, 0x3fb8aa3b, v92
	v_exp_f32_e32 v92, v92
	v_sub_f32_e32 v2, v2, v83
	v_mul_f32_e32 v2, 0x3fb8aa3b, v2
	v_exp_f32_e32 v2, v2
	v_mul_f32_e32 v92, v94, v92
	v_cndmask_b32_e64 v92, v92, 0, s[64:65]
	v_cvt_pk_bf16_f32 v93, v92, s0
	v_mul_f32_e32 v2, v95, v2
	ds_write_b16 v145, v93 offset:39936
	v_cndmask_b32_e64 v93, v2, 0, s[66:67]
	v_cvt_pk_bf16_f32 v2, v93, s0
	ds_write_b16 v146, v2 offset:39936
	v_sub_f32_e32 v2, v3, v80
	v_mul_f32_e32 v2, 0x3fb8aa3b, v2
	v_exp_f32_e32 v2, v2
	s_nop 0
	v_mul_f32_e32 v2, v88, v2
	v_cndmask_b32_e64 v2, v2, 0, s[26:27]
	v_add_f32_e32 v94, v97, v2
	v_cvt_pk_bf16_f32 v2, v2, s0
	ds_write_b16 v147, v2 offset:39968
	v_sub_f32_e32 v2, v3, v81
	v_mul_f32_e32 v2, 0x3fb8aa3b, v2
	v_exp_f32_e32 v2, v2
	s_nop 0
	v_mul_f32_e32 v2, v89, v2
	v_cndmask_b32_e64 v89, v2, 0, s[28:29]
	v_cvt_pk_bf16_f32 v2, v89, s0
	ds_write_b16 v148, v2 offset:39968
	v_sub_f32_e32 v2, v3, v82
	v_mul_f32_e32 v2, 0x3fb8aa3b, v2
	v_exp_f32_e32 v2, v2
	s_nop 0
	v_mul_f32_e32 v2, v90, v2
	v_cndmask_b32_e64 v90, v2, 0, s[78:79]
	v_cvt_pk_bf16_f32 v2, v90, s0
	ds_write_b16 v149, v2 offset:39968
	v_sub_f32_e32 v2, v3, v83
	v_mul_f32_e32 v2, 0x3fb8aa3b, v2
	v_exp_f32_e32 v2, v2
	s_nop 0
	v_mul_f32_e32 v2, v91, v2
	v_cndmask_b32_e64 v88, v2, 0, s[84:85]
	v_cvt_pk_bf16_f32 v2, v88, s0
	ds_write_b16 v159, v2 offset:39968
	ds_read2_b32 v[2:3], v96 offset0:32 offset1:48
	s_waitcnt lgkmcnt(0)
	v_sub_f32_e32 v91, v2, v80
	v_mul_f32_e32 v91, 0x3fb8aa3b, v91
	v_exp_f32_e32 v91, v91
	s_nop 0
	v_mul_f32_e32 v84, v84, v91
	v_cndmask_b32_e64 v84, v84, 0, s[92:93]
	v_add_f32_e32 v91, v94, v84
	v_cvt_pk_bf16_f32 v84, v84, s0
	ds_write_b16 v147, v84 offset:40000
	v_sub_f32_e32 v84, v2, v81
	v_mul_f32_e32 v84, 0x3fb8aa3b, v84
	v_exp_f32_e32 v84, v84
	s_nop 0
	v_mul_f32_e32 v84, v85, v84
	v_cndmask_b32_e64 v84, v84, 0, s[72:73]
	v_cvt_pk_bf16_f32 v85, v84, s0
	ds_write_b16 v148, v85 offset:40000
	v_sub_f32_e32 v85, v2, v82
	v_mul_f32_e32 v85, 0x3fb8aa3b, v85
	v_exp_f32_e32 v85, v85
	v_sub_f32_e32 v2, v2, v83
	v_mul_f32_e32 v2, 0x3fb8aa3b, v2
	v_exp_f32_e32 v2, v2
	v_mul_f32_e32 v85, v86, v85
	v_cndmask_b32_e64 v85, v85, 0, s[14:15]
	v_cvt_pk_bf16_f32 v86, v85, s0
	v_mul_f32_e32 v2, v87, v2
	ds_write_b16 v149, v86 offset:40000
	v_cndmask_b32_e64 v86, v2, 0, s[34:35]
	v_cvt_pk_bf16_f32 v2, v86, s0
	ds_write_b16 v159, v2 offset:40000
	v_sub_f32_e32 v2, v3, v80
	v_mul_f32_e32 v2, 0x3fb8aa3b, v2
	v_exp_f32_e32 v2, v2
	s_nop 0
	v_mul_f32_e32 v2, v76, v2
	v_cndmask_b32_e64 v2, v2, 0, s[8:9]
	v_add_f32_e32 v87, v91, v2
	v_cvt_pk_bf16_f32 v2, v2, s0
	ds_write_b16 v147, v2 offset:40032
	v_sub_f32_e32 v2, v3, v81
	v_mul_f32_e32 v2, 0x3fb8aa3b, v2
	v_exp_f32_e32 v2, v2
	s_nop 0
	v_mul_f32_e32 v2, v77, v2
	v_cndmask_b32_e64 v76, v2, 0, s[10:11]
	v_cvt_pk_bf16_f32 v2, v76, s0
	ds_write_b16 v148, v2 offset:40032
	v_sub_f32_e32 v2, v3, v82
	v_mul_f32_e32 v2, 0x3fb8aa3b, v2
	v_exp_f32_e32 v2, v2
	s_nop 0
	v_mul_f32_e32 v2, v78, v2
	v_cndmask_b32_e64 v77, v2, 0, s[18:19]
	v_cvt_pk_bf16_f32 v2, v77, s0
	ds_write_b16 v149, v2 offset:40032
	v_sub_f32_e32 v2, v3, v83
	v_mul_f32_e32 v2, 0x3fb8aa3b, v2
	v_exp_f32_e32 v2, v2
	v_and_b32_e32 v3, 64, v209
	v_add_u32_e32 v3, 64, v3
	v_mul_f32_e32 v2, v79, v2
	v_cndmask_b32_e64 v78, v2, 0, s[94:95]
	v_cvt_pk_bf16_f32 v2, v78, s0
	ds_write_b16 v159, v2 offset:40032
	v_xor_b32_e32 v2, 1, v209
	v_cmp_lt_i32_e32 vcc, v2, v3
	s_nop 1
	v_cndmask_b32_e32 v2, v209, v2, vcc
	v_lshlrev_b32_e32 v79, 2, v2
	s_nop 1
	v_mov_b32_dpp v83, v87 quad_perm:[1,0,3,2] row_mask:0xf bank_mask:0xf
	v_xor_b32_e32 v2, 2, v209
	v_cmp_lt_i32_e32 vcc, v2, v3
	s_waitcnt lgkmcnt(0)
	v_add_f32_e32 v83, v87, v83
	v_cndmask_b32_e32 v2, v209, v2, vcc
	v_lshlrev_b32_e32 v80, 2, v2
	s_nop 1
	v_mov_b32_dpp v87, v83 quad_perm:[2,3,0,1] row_mask:0xf bank_mask:0xf
	v_xor_b32_e32 v2, 4, v209
	v_cmp_lt_i32_e32 vcc, v2, v3
	s_waitcnt lgkmcnt(0)
	v_add_f32_e32 v83, v83, v87
	v_cndmask_b32_e32 v2, v209, v2, vcc
	v_lshlrev_b32_e32 v81, 2, v2
	s_nop 1
	v_mov_b32_dpp v87, v83 quad_perm:[3,2,1,0] row_mask:0xf bank_mask:0xf
	s_nop 1
	v_mov_b32_dpp v87, v87 row_half_mirror row_mask:0xf bank_mask:0xf
	v_xor_b32_e32 v2, 8, v209
	v_cmp_lt_i32_e32 vcc, v2, v3
	s_waitcnt lgkmcnt(0)
	v_add_f32_e32 v83, v83, v87
	v_cndmask_b32_e32 v2, v209, v2, vcc
	v_lshlrev_b32_e32 v82, 2, v2
	s_nop 1
	v_mov_b32_dpp v87, v83 row_ror:8 row_mask:0xf bank_mask:0xf
	v_lshl_add_u64 v[2:3], s[76:77], 4, v[118:119]
	s_and_saveexec_b64 s[38:39], s[68:69]
	s_cbranch_execz .LBB0_653
	s_waitcnt lgkmcnt(0)
	v_add_f32_e32 v83, v83, v87
	v_cndmask_b32_e64 v87, v160, v127, s[70:71]
	v_or_b32_e32 v94, v87, v171
	v_ashrrev_i32_e32 v95, 31, v94
	v_lshlrev_b64 v[94:95], 5, v[94:95]
	v_lshl_add_u64 v[94:95], v[2:3], 0, v[94:95]
	global_store_dword v[94:95], v83, off
.LBB0_653:
	s_or_b64 exec, exec, s[38:39]
	v_add_f32_e32 v0, 0, v0
	v_add_f32_e32 v0, v0, v89
	v_add_f32_e32 v0, v0, v84
	v_add_f32_e32 v0, v0, v76
	s_nop 1
	v_mov_b32_dpp v76, v0 quad_perm:[1,0,3,2] row_mask:0xf bank_mask:0xf
	s_waitcnt lgkmcnt(0)
	v_add_f32_e32 v0, v0, v76
	s_nop 1
	v_mov_b32_dpp v76, v0 quad_perm:[2,3,0,1] row_mask:0xf bank_mask:0xf
	s_waitcnt lgkmcnt(0)
	v_add_f32_e32 v0, v0, v76
	s_nop 1
	v_mov_b32_dpp v76, v0 quad_perm:[3,2,1,0] row_mask:0xf bank_mask:0xf
	s_nop 1
	v_mov_b32_dpp v76, v76 row_half_mirror row_mask:0xf bank_mask:0xf
	s_waitcnt lgkmcnt(0)
	v_add_f32_e32 v0, v0, v76
	s_nop 1
	v_mov_b32_dpp v76, v0 row_ror:8 row_mask:0xf bank_mask:0xf
	s_and_saveexec_b64 s[38:39], s[68:69]
	s_cbranch_execz .LBB0_655
	s_waitcnt lgkmcnt(0)
	v_add_f32_e32 v0, v0, v76
	v_cndmask_b32_e64 v76, v161, v139, s[70:71]
	v_or_b32_e32 v94, v76, v171
	v_ashrrev_i32_e32 v95, 31, v94
	v_lshlrev_b64 v[94:95], 5, v[94:95]
	v_lshl_add_u64 v[94:95], v[2:3], 0, v[94:95]
	global_store_dword v[94:95], v0, off
.LBB0_655:
	s_or_b64 exec, exec, s[38:39]
	v_add_f32_e32 v0, 0, v92
	v_add_f32_e32 v0, v0, v90
	v_add_f32_e32 v0, v0, v85
	v_add_f32_e32 v0, v0, v77
	s_waitcnt lgkmcnt(0)
	s_nop 1
	v_mov_b32_dpp v76, v0 quad_perm:[1,0,3,2] row_mask:0xf bank_mask:0xf
	s_waitcnt lgkmcnt(0)
	v_add_f32_e32 v0, v0, v76
	s_nop 1
	v_mov_b32_dpp v76, v0 quad_perm:[2,3,0,1] row_mask:0xf bank_mask:0xf
	s_waitcnt lgkmcnt(0)
	v_add_f32_e32 v0, v0, v76
	s_nop 1
	v_mov_b32_dpp v76, v0 quad_perm:[3,2,1,0] row_mask:0xf bank_mask:0xf
	s_nop 1
	v_mov_b32_dpp v76, v76 row_half_mirror row_mask:0xf bank_mask:0xf
	s_waitcnt lgkmcnt(0)
	v_add_f32_e32 v0, v0, v76
	s_nop 1
	v_mov_b32_dpp v76, v0 row_ror:8 row_mask:0xf bank_mask:0xf
	s_and_saveexec_b64 s[38:39], s[68:69]
	s_cbranch_execz .LBB0_657
	s_waitcnt lgkmcnt(0)
	v_add_f32_e32 v0, v0, v76
	v_cndmask_b32_e64 v76, v162, v140, s[70:71]
	v_or_b32_e32 v76, v76, v171
	v_ashrrev_i32_e32 v77, 31, v76
	v_lshlrev_b64 v[76:77], 5, v[76:77]
	v_lshl_add_u64 v[76:77], v[2:3], 0, v[76:77]
	global_store_dword v[76:77], v0, off
.LBB0_657:
	s_or_b64 exec, exec, s[38:39]
	v_add_f32_e32 v0, 0, v93
	v_add_f32_e32 v0, v0, v88
	v_add_f32_e32 v0, v0, v86
	v_add_f32_e32 v0, v0, v78
	s_waitcnt lgkmcnt(0)
	s_nop 1
	v_mov_b32_dpp v76, v0 quad_perm:[1,0,3,2] row_mask:0xf bank_mask:0xf
	s_waitcnt lgkmcnt(0)
	v_add_f32_e32 v0, v0, v76
	s_nop 1
	v_mov_b32_dpp v76, v0 quad_perm:[2,3,0,1] row_mask:0xf bank_mask:0xf
	s_waitcnt lgkmcnt(0)
	v_add_f32_e32 v0, v0, v76
	s_nop 1
	v_mov_b32_dpp v76, v0 quad_perm:[3,2,1,0] row_mask:0xf bank_mask:0xf
	s_nop 1
	v_mov_b32_dpp v76, v76 row_half_mirror row_mask:0xf bank_mask:0xf
	s_waitcnt lgkmcnt(0)
	v_add_f32_e32 v0, v0, v76
	s_nop 1
	v_mov_b32_dpp v76, v0 row_ror:8 row_mask:0xf bank_mask:0xf
	s_and_saveexec_b64 s[38:39], s[68:69]
	s_cbranch_execz .LBB0_629
	s_waitcnt lgkmcnt(0)
	v_add_f32_e32 v0, v0, v76
	v_cndmask_b32_e64 v76, v163, v141, s[70:71]
	v_or_b32_e32 v76, v76, v171
	v_ashrrev_i32_e32 v77, 31, v76
	v_lshlrev_b64 v[76:77], 5, v[76:77]
	v_lshl_add_u64 v[2:3], v[2:3], 0, v[76:77]
	global_store_dword v[2:3], v0, off
	s_branch .LBB0_629

.LBB0_683:
	s_or_b64 exec, exec, s[14:15]
	v_lshl_add_u64 v[16:17], v[16:17], 0, v[0:1]
	global_load_dwordx4 v[24:27], v[16:17], off
	global_load_dwordx4 v[28:31], v[16:17], off offset:1024
	global_load_dwordx4 v[32:35], v[16:17], off offset:2048
	global_load_dwordx4 v[36:39], v[16:17], off offset:3072
	s_load_dwordx2 s[14:15], s[54:55], 0x130
	v_min_i32_e32 v13, 0x8000, v4
	v_ashrrev_i32_e32 v13, 13, v13
	v_mul_hi_i32_i24_e32 v17, 0x6000, v13
	v_mul_i32_i24_e32 v16, 0x6000, v13
	s_waitcnt lgkmcnt(0)
	v_lshl_add_u64 v[16:17], s[14:15], 0, v[16:17]
	s_mov_b64 s[14:15], 0x1000
	v_lshl_add_u64 v[48:49], v[16:17], 0, s[14:15]
	v_lshl_add_u64 v[40:41], v[48:49], 0, v[0:1]
	global_load_dwordx4 v[40:43], v[40:41], off
	v_lshl_add_u64 v[50:51], v[16:17], 0, v[0:1]
	global_load_dwordx4 v[44:47], v[50:51], off
	v_mov_b32_e32 v97, v1
	v_mov_b32_e32 v96, v8
	v_lshl_add_u64 v[90:91], v[48:49], 0, v[96:97]
	global_load_dwordx4 v[66:69], v[90:91], off
	v_mov_b32_e32 v96, v10
	v_lshl_add_u64 v[92:93], v[48:49], 0, v[96:97]
	global_load_dwordx4 v[70:73], v[92:93], off
	v_mov_b32_e32 v96, v12
	v_lshl_add_u64 v[94:95], v[48:49], 0, v[96:97]
	global_load_dwordx4 v[74:77], v[94:95], off
	global_load_dwordx4 v[78:81], v[50:51], off offset:1024
	global_load_dwordx4 v[82:85], v[50:51], off offset:2048
	global_load_dwordx4 v[86:89], v[50:51], off offset:3072
	v_lshlrev_b64 v[14:15], 11, v[14:15]
	v_lshl_add_u64 v[4:5], v[4:5], 0, s[8:9]
	s_mov_b32 s1, 0x83ff
	v_lshl_add_u64 v[6:7], v[6:7], 0, s[10:11]
	s_waitcnt vmcnt(11)
	v_add_f32_e32 v9, 0, v24
	v_add_f32_e32 v9, v25, v9
	v_add_f32_e32 v9, v26, v9
	v_add_f32_e32 v9, v27, v9
	s_waitcnt vmcnt(10)
	v_add_f32_e32 v9, v28, v9
	v_add_f32_e32 v9, v29, v9
	v_add_f32_e32 v9, v30, v9
	v_add_f32_e32 v9, v31, v9
	s_waitcnt vmcnt(9)
	v_add_f32_e32 v9, v32, v9
	v_add_f32_e32 v9, v33, v9
	v_add_f32_e32 v9, v34, v9
	v_add_f32_e32 v9, v35, v9
	s_waitcnt vmcnt(8)
	v_add_f32_e32 v9, v36, v9
	v_add_f32_e32 v9, v37, v9
	v_add_f32_e32 v9, v38, v9
	v_add_f32_e32 v9, v39, v9
	v_mov_b32_e32 v11, v9
	s_nop 1
	v_permlane32_swap_b32_e32 v11, v9
	s_waitcnt lgkmcnt(0)
	v_add_f32_e32 v9, v9, v11
	v_mov_b32_e32 v11, v9
	s_nop 1
	v_permlane16_swap_b32_e32 v11, v9
	s_waitcnt lgkmcnt(0)
	v_add_f32_e32 v9, v9, v11
	s_nop 1
	v_mov_b32_dpp v11, v9 row_ror:8 row_mask:0xf bank_mask:0xf
	s_waitcnt lgkmcnt(0)
	v_add_f32_e32 v9, v9, v11
	s_nop 1
	v_mov_b32_dpp v11, v9 quad_perm:[3,2,1,0] row_mask:0xf bank_mask:0xf
	s_nop 1
	v_mov_b32_dpp v11, v11 row_half_mirror row_mask:0xf bank_mask:0xf
	s_waitcnt lgkmcnt(0)
	v_add_f32_e32 v9, v9, v11
	s_nop 1
	v_mov_b32_dpp v11, v9 quad_perm:[2,3,0,1] row_mask:0xf bank_mask:0xf
	s_waitcnt lgkmcnt(0)
	v_add_f32_e32 v9, v9, v11
	s_nop 1
	v_mov_b32_dpp v11, v9 quad_perm:[1,0,3,2] row_mask:0xf bank_mask:0xf
	s_waitcnt lgkmcnt(0)
	v_add_f32_e32 v9, v9, v11
	v_mul_f32_e32 v16, 0x3a800000, v9
	v_pk_add_f32 v[24:25], v[24:25], v[16:17] op_sel_hi:[1,0] neg_lo:[0,1] neg_hi:[0,1]
	v_pk_add_f32 v[26:27], v[26:27], v[16:17] op_sel_hi:[1,0] neg_lo:[0,1] neg_hi:[0,1]
	v_pk_mul_f32 v[52:53], v[24:25], v[24:25]
	v_pk_add_f32 v[30:31], v[30:31], v[16:17] op_sel_hi:[1,0] neg_lo:[0,1] neg_hi:[0,1]
	v_pk_add_f32 v[28:29], v[28:29], v[16:17] op_sel_hi:[1,0] neg_lo:[0,1] neg_hi:[0,1]
	v_pk_add_f32 v[34:35], v[34:35], v[16:17] op_sel_hi:[1,0] neg_lo:[0,1] neg_hi:[0,1]
	v_pk_add_f32 v[32:33], v[32:33], v[16:17] op_sel_hi:[1,0] neg_lo:[0,1] neg_hi:[0,1]
	v_pk_add_f32 v[38:39], v[38:39], v[16:17] op_sel_hi:[1,0] neg_lo:[0,1] neg_hi:[0,1]
	v_pk_add_f32 v[36:37], v[36:37], v[16:17] op_sel_hi:[1,0] neg_lo:[0,1] neg_hi:[0,1]
	v_pk_mul_f32 v[16:17], v[26:27], v[26:27]
	v_add_f32_e32 v9, v52, v53
	v_add_f32_e32 v9, v16, v9
	v_pk_mul_f32 v[56:57], v[28:29], v[28:29]
	v_add_f32_e32 v9, v17, v9
	v_add_f32_e32 v9, v56, v9
	v_pk_mul_f32 v[54:55], v[30:31], v[30:31]
	v_add_f32_e32 v9, v57, v9
	v_add_f32_e32 v9, v54, v9
	v_pk_mul_f32 v[60:61], v[32:33], v[32:33]
	v_add_f32_e32 v9, v55, v9
	v_add_f32_e32 v9, v60, v9
	v_pk_mul_f32 v[58:59], v[34:35], v[34:35]
	v_add_f32_e32 v9, v61, v9
	v_add_f32_e32 v9, v58, v9
	v_pk_mul_f32 v[64:65], v[36:37], v[36:37]
	v_add_f32_e32 v9, v59, v9
	v_add_f32_e32 v9, v64, v9
	v_pk_mul_f32 v[62:63], v[38:39], v[38:39]
	v_add_f32_e32 v9, v65, v9
	v_add_f32_e32 v9, v62, v9
	v_add_f32_e32 v9, v63, v9
	v_mov_b32_e32 v11, v9
	s_nop 1
	v_permlane32_swap_b32_e32 v11, v9
	v_lshl_add_u64 v[52:53], v[2:3], 0, v[14:15]
	s_waitcnt lgkmcnt(0)
	v_add_f32_e32 v9, v9, v11
	v_mov_b32_e32 v11, v9
	s_nop 1
	v_permlane16_swap_b32_e32 v11, v9
	s_waitcnt lgkmcnt(0)
	v_add_f32_e32 v9, v9, v11
	s_nop 1
	v_mov_b32_dpp v11, v9 row_ror:8 row_mask:0xf bank_mask:0xf
	s_waitcnt lgkmcnt(0)
	v_add_f32_e32 v9, v9, v11
	s_nop 1
	v_mov_b32_dpp v11, v9 quad_perm:[3,2,1,0] row_mask:0xf bank_mask:0xf
	s_nop 1
	v_mov_b32_dpp v11, v11 row_half_mirror row_mask:0xf bank_mask:0xf
	s_waitcnt lgkmcnt(0)
	v_add_f32_e32 v9, v9, v11
	s_nop 1
	v_mov_b32_dpp v11, v9 quad_perm:[2,3,0,1] row_mask:0xf bank_mask:0xf
	s_waitcnt lgkmcnt(0)
	v_add_f32_e32 v11, v9, v11
	s_nop 1
	v_mov_b32_dpp v13, v11 quad_perm:[1,0,3,2] row_mask:0xf bank_mask:0xf
	v_mov_b32_e32 v9, v1
	s_waitcnt lgkmcnt(0)
	v_add_f32_e32 v11, v11, v13
	v_fmamk_f32 v11, v11, 0x3a800000, v208
	v_mul_f32_e32 v13, 0x4b800000, v11
	v_cmp_gt_f32_e32 vcc, s5, v11
	s_nop 1
	v_cndmask_b32_e32 v11, v11, v13, vcc
	v_rsq_f32_e32 v11, v11
	v_mov_b32_e32 v13, v1
	v_mul_f32_e32 v9, 0x45800000, v11
	v_cndmask_b32_e32 v98, v11, v9, vcc
	v_cmp_lt_i32_e32 vcc, s1, v4
	s_or_b64 s[12:13], vcc, s[12:13]
	s_waitcnt vmcnt(0)
	v_pk_mul_f32 v[24:25], v[24:25], v[98:99] op_sel_hi:[1,0]
	v_pk_mul_f32 v[26:27], v[26:27], v[98:99] op_sel_hi:[1,0]
	v_pk_add_f32 v[40:41], v[40:41], 1.0 op_sel_hi:[1,0]
	v_pk_add_f32 v[42:43], v[42:43], 1.0 op_sel_hi:[1,0]
	v_pk_fma_f32 v[40:41], v[40:41], v[24:25], v[44:45]
	v_pk_fma_f32 v[42:43], v[42:43], v[26:27], v[46:47]
	v_cvt_pk_bf16_f32 v40, v40, v41
	v_cvt_pk_bf16_f32 v41, v42, v43
	global_store_dwordx2 v[52:53], v[40:41], off
	v_pk_mul_f32 v[28:29], v[28:29], v[98:99] op_sel_hi:[1,0]
	v_pk_mul_f32 v[30:31], v[30:31], v[98:99] op_sel_hi:[1,0]
	v_pk_add_f32 v[66:67], v[66:67], 1.0 op_sel_hi:[1,0]
	v_pk_add_f32 v[68:69], v[68:69], 1.0 op_sel_hi:[1,0]
	v_pk_fma_f32 v[66:67], v[66:67], v[28:29], v[78:79]
	v_pk_fma_f32 v[68:69], v[68:69], v[30:31], v[80:81]
	v_cvt_pk_bf16_f32 v66, v66, v67
	v_cvt_pk_bf16_f32 v67, v68, v69
	global_store_dwordx2 v[52:53], v[66:67], off offset:512
	v_pk_mul_f32 v[32:33], v[32:33], v[98:99] op_sel_hi:[1,0]
	v_pk_mul_f32 v[34:35], v[34:35], v[98:99] op_sel_hi:[1,0]
	v_pk_add_f32 v[70:71], v[70:71], 1.0 op_sel_hi:[1,0]
	v_pk_add_f32 v[72:73], v[72:73], 1.0 op_sel_hi:[1,0]
	v_pk_fma_f32 v[70:71], v[70:71], v[32:33], v[82:83]
	v_pk_fma_f32 v[72:73], v[72:73], v[34:35], v[84:85]
	v_cvt_pk_bf16_f32 v70, v70, v71
	v_cvt_pk_bf16_f32 v71, v72, v73
	global_store_dwordx2 v[52:53], v[70:71], off offset:1024
	v_pk_mul_f32 v[36:37], v[36:37], v[98:99] op_sel_hi:[1,0]
	v_pk_mul_f32 v[38:39], v[38:39], v[98:99] op_sel_hi:[1,0]
	v_pk_add_f32 v[74:75], v[74:75], 1.0 op_sel_hi:[1,0]
	v_pk_add_f32 v[76:77], v[76:77], 1.0 op_sel_hi:[1,0]
	v_pk_fma_f32 v[74:75], v[74:75], v[36:37], v[86:87]
	v_pk_fma_f32 v[76:77], v[76:77], v[38:39], v[88:89]
	v_cvt_pk_bf16_f32 v74, v74, v75
	v_cvt_pk_bf16_f32 v75, v76, v77
	global_store_dwordx2 v[52:53], v[74:75], off offset:1536
	s_andn2_b64 exec, exec, s[12:13]
	s_cbranch_execz .LBB0_686
